# loads hoisted to the top of 10 straight-line blocks (norm1 split-K fix-up, final norm, mLSTM, mixers): fewer serialized round trips
# speedup vs baseline: 1.0174x; 1.0013x over previous
.LBB0_153:
	s_ashr_i32 s7, s12, 10
	s_add_i32 s7, s7, 1
	s_and_b64 s[12:13], s[4:5], exec
	s_cselect_b32 s7, s7, 0
	s_and_b64 s[14:15], s[10:11], s[4:5]
	v_cndmask_b32_e64 v34, 0, 1, s[14:15]
	s_mul_hi_i32 s13, s7, 0x3000
	v_cmp_ne_u32_e64 s[4:5], 1, v34
	s_andn2_b64 vcc, exec, s[14:15]
	s_mul_i32 s12, s7, 0x3000
	s_cbranch_vccnz .LBB0_155
	s_lshl_b64 s[14:15], s[46:47], 12
	v_lshl_add_u64 v[70:71], v[138:139], 0, s[14:15]
	global_load_dwordx4 v[50:53], v[70:71], off
	s_mov_b32 s7, 0x800000
	v_add_co_u32_e32 v72, vcc, s7, v70
	s_mov_b32 s7, 0x1000000
	s_nop 0
	v_addc_co_u32_e32 v73, vcc, 0, v71, vcc
	global_load_dwordx4 v[54:57], v[72:73], off
	v_add_co_u32_e32 v74, vcc, s7, v70
	s_nop 0
	s_nop 0
	v_addc_co_u32_e32 v75, vcc, 0, v71, vcc
	global_load_dwordx4 v[58:61], v[74:75], off
	s_mov_b32 s7, 0x1800000
	v_add_co_u32_e32 v76, vcc, s7, v70
	s_lshl_b64 s[14:15], s[12:13], 2
	s_nop 0
	v_addc_co_u32_e32 v77, vcc, 0, v71, vcc
	global_load_dwordx4 v[62:65], v[76:77], off
	global_load_dwordx4 v[46:49], v[70:71], off offset:1024
	global_load_dwordx4 v[34:37], v[72:73], off offset:1024
	global_load_dwordx4 v[38:41], v[74:75], off offset:1024
	global_load_dwordx4 v[42:45], v[76:77], off offset:1024
	s_nop 0
	s_nop 0
	s_nop 0
	s_add_u32 s14, s8, s14
	s_addc_u32 s15, s9, s15
	global_load_dwordx4 v[82:85], v0, s[14:15]
	global_load_dwordx4 v[86:89], v0, s[14:15] offset:16
	global_load_dwordx4 v[90:93], v0, s[14:15] offset:2048
	global_load_dwordx4 v[94:97], v[76:77], off offset:2048
	global_load_dwordx4 v[98:101], v0, s[14:15] offset:2064
	global_load_dwordx4 v[102:105], v[70:71], off offset:2048
	global_load_dwordx4 v[106:109], v[72:73], off offset:2048
	global_load_dwordx4 v[110:113], v[74:75], off offset:2048
	global_load_dwordx4 v[114:117], v[70:71], off offset:3072
	global_load_dwordx4 v[118:121], v[72:73], off offset:3072
	s_nop 0
	s_waitcnt vmcnt(17)
	v_and_b32_e32 v66, 0xffff0000, v50
	s_waitcnt vmcnt(16)
	v_and_b32_e32 v68, 0xffff0000, v54
	v_and_b32_e32 v78, 0xffff0000, v55
	v_lshlrev_b32_e32 v50, 16, v50
	s_waitcnt vmcnt(15)
	v_and_b32_e32 v67, 0xffff0000, v58
	v_lshlrev_b32_e32 v54, 16, v54
	s_waitcnt vmcnt(14)
	v_and_b32_e32 v69, 0xffff0000, v62
	v_pk_add_f32 v[66:67], v[66:67], v[68:69]
	v_and_b32_e32 v68, 0xffff0000, v51
	v_and_b32_e32 v69, 0xffff0000, v59
	v_and_b32_e32 v79, 0xffff0000, v63
	v_pk_add_f32 v[68:69], v[68:69], v[78:79]
	v_add_f32_e32 v78, v54, v50
	v_lshlrev_b32_e32 v50, 16, v58
	v_lshlrev_b32_e32 v54, 16, v62
	v_add_f32_e32 v80, v54, v50
	v_lshlrev_b32_e32 v50, 16, v51
	v_lshlrev_b32_e32 v51, 16, v55
	v_add_f32_e32 v50, v51, v50
	v_lshlrev_b32_e32 v51, 16, v59
	v_lshlrev_b32_e32 v54, 16, v63
	v_mov_b32_e32 v79, v66
	v_mov_b32_e32 v81, v67
	v_add_f32_e32 v54, v54, v51
	v_mov_b32_e32 v51, v68
	v_mov_b32_e32 v55, v69
	s_nop 0
	v_pk_add_f32 v[58:59], v[78:79], v[80:81]
	v_pk_add_f32 v[50:51], v[50:51], v[54:55]
	v_lshlrev_b32_e32 v62, 16, v60
	v_lshlrev_b32_e32 v63, 16, v57
	v_and_b32_e32 v54, 0xffff0000, v56
	v_and_b32_e32 v55, 0xffff0000, v64
	v_lshlrev_b32_e32 v64, 16, v64
	v_add_f32_e32 v62, v64, v62
	s_waitcnt vmcnt(11)
	v_lshlrev_b32_e32 v79, 16, v41
	v_lshlrev_b32_e32 v81, 16, v37
	v_lshlrev_b32_e32 v78, 16, v49
	s_waitcnt vmcnt(9)
	v_pk_fma_f32 v[30:31], v[82:83], v[58:59], v[30:31]
	v_pk_fma_f32 v[32:33], v[84:85], v[50:51], v[32:33]
	v_lshlrev_b32_e32 v58, 16, v52
	v_lshlrev_b32_e32 v59, 16, v53
	v_and_b32_e32 v50, 0xffff0000, v52
	v_and_b32_e32 v52, 0xffff0000, v53
	v_and_b32_e32 v51, 0xffff0000, v60
	v_and_b32_e32 v53, 0xffff0000, v61
	v_lshlrev_b32_e32 v60, 16, v56
	v_and_b32_e32 v56, 0xffff0000, v57
	v_and_b32_e32 v57, 0xffff0000, v65
	v_pk_add_f32 v[54:55], v[50:51], v[54:55]
	v_pk_add_f32 v[56:57], v[52:53], v[56:57]
	s_nop 0
	v_lshlrev_b32_e32 v61, 16, v61
	v_lshlrev_b32_e32 v65, 16, v65
	v_add_f32_e32 v58, v60, v58
	v_add_f32_e32 v60, v63, v59
	v_add_f32_e32 v64, v65, v61
	v_mov_b32_e32 v59, v54
	v_mov_b32_e32 v63, v55
	v_mov_b32_e32 v61, v56
	v_mov_b32_e32 v65, v57
	s_nop 0
	v_pk_add_f32 v[58:59], v[58:59], v[62:63]
	v_pk_add_f32 v[60:61], v[60:61], v[64:65]
	s_nop 0
	s_nop 0
	v_lshlrev_b32_e32 v80, 16, v45
	s_waitcnt vmcnt(8)
	v_pk_fma_f32 v[26:27], v[86:87], v[58:59], v[26:27]
	v_pk_fma_f32 v[28:29], v[88:89], v[60:61], v[28:29]
	v_and_b32_e32 v53, 0xffff0000, v38
	v_and_b32_e32 v52, 0xffff0000, v46
	v_and_b32_e32 v59, 0xffff0000, v42
	v_and_b32_e32 v58, 0xffff0000, v34
	v_lshlrev_b32_e32 v50, 16, v34
	v_pk_add_f32 v[52:53], v[52:53], v[58:59]
	v_and_b32_e32 v59, 0xffff0000, v39
	v_and_b32_e32 v58, 0xffff0000, v47
	v_and_b32_e32 v61, 0xffff0000, v43
	v_and_b32_e32 v60, 0xffff0000, v35
	v_lshlrev_b32_e32 v34, 16, v38
	v_lshlrev_b32_e32 v38, 16, v42
	v_pk_add_f32 v[58:59], v[58:59], v[60:61]
	v_add_f32_e32 v60, v38, v34
	v_lshlrev_b32_e32 v34, 16, v35
	v_lshlrev_b32_e32 v35, 16, v47
	v_lshlrev_b32_e32 v51, 16, v46
	v_add_f32_e32 v34, v34, v35
	v_lshlrev_b32_e32 v35, 16, v39
	v_lshlrev_b32_e32 v38, 16, v43
	v_add_f32_e32 v50, v50, v51
	v_mov_b32_e32 v51, v52
	v_mov_b32_e32 v61, v53
	v_add_f32_e32 v38, v38, v35
	v_mov_b32_e32 v35, v58
	v_mov_b32_e32 v39, v59
	v_pk_add_f32 v[46:47], v[50:51], v[60:61]
	v_pk_add_f32 v[34:35], v[34:35], v[38:39]
	s_waitcnt vmcnt(7)
	v_pk_fma_f32 v[22:23], v[90:91], v[46:47], v[22:23]
	s_nop 0
	v_pk_fma_f32 v[24:25], v[92:93], v[34:35], v[24:25]
	s_nop 0
	s_nop 0
	v_and_b32_e32 v34, 0xffff0000, v48
	v_lshlrev_b32_e32 v47, 16, v40
	v_and_b32_e32 v35, 0xffff0000, v40
	v_and_b32_e32 v39, 0xffff0000, v41
	v_and_b32_e32 v41, 0xffff0000, v44
	v_and_b32_e32 v40, 0xffff0000, v36
	v_lshlrev_b32_e32 v46, 16, v48
	v_lshlrev_b32_e32 v48, 16, v44
	v_lshlrev_b32_e32 v44, 16, v36
	v_pk_add_f32 v[34:35], v[34:35], v[40:41]
	v_and_b32_e32 v38, 0xffff0000, v49
	v_and_b32_e32 v43, 0xffff0000, v45
	v_and_b32_e32 v42, 0xffff0000, v37
	v_add_f32_e32 v36, v44, v46
	v_add_f32_e32 v40, v48, v47
	v_mov_b32_e32 v37, v34
	v_mov_b32_e32 v41, v35
	v_pk_add_f32 v[38:39], v[38:39], v[42:43]
	v_pk_add_f32 v[40:41], v[36:37], v[40:41]
	s_nop 0
	s_waitcnt vmcnt(5)
	v_pk_fma_f32 v[18:19], v[98:99], v[40:41], v[18:19]
	v_add_f32_e32 v66, v81, v78
	v_add_f32_e32 v70, v80, v79
	v_mov_b32_e32 v67, v38
	v_mov_b32_e32 v71, v39
	v_pk_add_f32 v[66:67], v[66:67], v[70:71]
	s_nop 0
	v_pk_fma_f32 v[20:21], v[100:101], v[66:67], v[20:21]
	global_load_dwordx4 v[42:45], v[74:75], off offset:3072
	global_load_dwordx4 v[38:41], v[76:77], off offset:3072
	global_load_dwordx4 v[122:125], v145, s[14:15]
	global_load_dwordx4 v[126:129], v145, s[14:15] offset:16
	global_load_dwordx4 v[150:153], v146, s[14:15]
	global_load_dwordx4 v[154:157], v146, s[14:15] offset:16
	v_and_b32_e32 v71, 0xffff0000, v94
	v_and_b32_e32 v73, 0xffff0000, v95
	s_nop 0
	v_lshlrev_b32_e32 v75, 16, v97
	s_waitcnt vmcnt(10)
	v_lshlrev_b32_e32 v67, 16, v102
	s_waitcnt vmcnt(9)
	v_lshlrev_b32_e32 v66, 16, v106
	v_add_f32_e32 v68, v66, v67
	s_waitcnt vmcnt(8)
	v_and_b32_e32 v67, 0xffff0000, v110
	v_and_b32_e32 v66, 0xffff0000, v102
	v_and_b32_e32 v70, 0xffff0000, v106
	v_pk_add_f32 v[70:71], v[66:67], v[70:71]
	v_and_b32_e32 v67, 0xffff0000, v111
	v_and_b32_e32 v66, 0xffff0000, v103
	v_and_b32_e32 v72, 0xffff0000, v107
	v_lshlrev_b32_e32 v50, 16, v110
	v_lshlrev_b32_e32 v54, 16, v94
	v_pk_add_f32 v[66:67], v[66:67], v[72:73]
	v_add_f32_e32 v72, v54, v50
	v_mov_b32_e32 v69, v70
	v_mov_b32_e32 v73, v71
	v_pk_add_f32 v[68:69], v[68:69], v[72:73]
	s_nop 0
	v_lshlrev_b32_e32 v50, 16, v107
	v_lshlrev_b32_e32 v103, 16, v103
	v_add_f32_e32 v50, v50, v103
	v_lshlrev_b32_e32 v51, 16, v111
	v_lshlrev_b32_e32 v54, 16, v95
	v_add_f32_e32 v54, v54, v51
	v_mov_b32_e32 v51, v66
	v_mov_b32_e32 v55, v67
	v_pk_add_f32 v[50:51], v[50:51], v[54:55]
	v_and_b32_e32 v54, 0xffff0000, v104
	v_and_b32_e32 v58, 0xffff0000, v105
	v_and_b32_e32 v55, 0xffff0000, v112
	v_and_b32_e32 v59, 0xffff0000, v113
	v_lshlrev_b32_e32 v74, 16, v113
	v_and_b32_e32 v61, 0xffff0000, v96
	v_and_b32_e32 v63, 0xffff0000, v97
	v_lshlrev_b32_e32 v65, 16, v109
	v_and_b32_e32 v62, 0xffff0000, v109
	v_pk_add_f32 v[58:59], v[58:59], v[62:63]
	s_waitcnt vmcnt(3)
	v_pk_fma_f32 v[14:15], v[122:123], v[68:69], v[14:15]
	s_nop 0
	v_pk_fma_f32 v[16:17], v[124:125], v[50:51], v[16:17]
	v_lshlrev_b32_e32 v70, 16, v104
	v_lshlrev_b32_e32 v71, 16, v105
	v_lshlrev_b32_e32 v72, 16, v112
	v_and_b32_e32 v60, 0xffff0000, v108
	s_nop 0
	v_lshlrev_b32_e32 v73, 16, v96
	v_lshlrev_b32_e32 v64, 16, v108
	v_pk_add_f32 v[60:61], v[54:55], v[60:61]
	s_nop 0
	v_add_f32_e32 v62, v64, v70
	v_add_f32_e32 v64, v73, v72
	v_add_f32_e32 v70, v65, v71
	v_add_f32_e32 v72, v75, v74
	v_mov_b32_e32 v63, v60
	v_mov_b32_e32 v65, v61
	v_mov_b32_e32 v71, v58
	v_mov_b32_e32 v73, v59
	v_pk_add_f32 v[60:61], v[62:63], v[64:65]
	v_pk_add_f32 v[58:59], v[70:71], v[72:73]
	v_and_b32_e32 v65, 0xffff0000, v38
	v_and_b32_e32 v64, 0xffff0000, v118
	v_and_b32_e32 v63, 0xffff0000, v42
	v_and_b32_e32 v62, 0xffff0000, v114
	v_pk_add_f32 v[62:63], v[62:63], v[64:65]
	s_waitcnt vmcnt(2)
	v_pk_fma_f32 v[10:11], v[126:127], v[60:61], v[10:11]
	v_pk_fma_f32 v[12:13], v[128:129], v[58:59], v[12:13]
	v_lshlrev_b32_e32 v58, 16, v118
	v_lshlrev_b32_e32 v59, 16, v114
	v_lshlrev_b32_e32 v60, 16, v38
	v_lshlrev_b32_e32 v34, 16, v119
	v_lshlrev_b32_e32 v38, 16, v115
	v_add_f32_e32 v58, v58, v59
	v_lshlrev_b32_e32 v59, 16, v42
	v_add_f32_e32 v34, v34, v38
	v_lshlrev_b32_e32 v38, 16, v43
	v_lshlrev_b32_e32 v42, 16, v39
	v_add_f32_e32 v38, v42, v38
	v_and_b32_e32 v43, 0xffff0000, v43
	v_and_b32_e32 v42, 0xffff0000, v115
	v_and_b32_e32 v47, 0xffff0000, v39
	v_and_b32_e32 v46, 0xffff0000, v119
	v_pk_add_f32 v[42:43], v[42:43], v[46:47]
	v_lshlrev_b32_e32 v35, 16, v116
	v_lshlrev_b32_e32 v47, 16, v120
	v_add_f32_e32 v64, v47, v35
	v_lshlrev_b32_e32 v35, 16, v44
	v_and_b32_e32 v47, 0xffff0000, v44
	v_lshlrev_b32_e32 v44, 16, v40
	v_lshlrev_b32_e32 v39, 16, v117
	v_add_f32_e32 v44, v44, v35
	v_lshlrev_b32_e32 v35, 16, v121
	v_and_b32_e32 v46, 0xffff0000, v116
	v_and_b32_e32 v48, 0xffff0000, v117
	v_and_b32_e32 v49, 0xffff0000, v45
	v_lshlrev_b32_e32 v45, 16, v45
	v_and_b32_e32 v67, 0xffff0000, v40
	v_and_b32_e32 v66, 0xffff0000, v120
	v_add_f32_e32 v36, v35, v39
	v_lshlrev_b32_e32 v35, 16, v41
	v_pk_add_f32 v[46:47], v[46:47], v[66:67]
	v_add_f32_e32 v40, v35, v45
	v_and_b32_e32 v67, 0xffff0000, v41
	v_and_b32_e32 v66, 0xffff0000, v121
	v_mov_b32_e32 v35, v42
	v_mov_b32_e32 v39, v43
	v_pk_add_f32 v[48:49], v[48:49], v[66:67]
	v_pk_add_f32 v[34:35], v[34:35], v[38:39]
	v_mov_b32_e32 v65, v46
	v_mov_b32_e32 v45, v47
	v_add_f32_e32 v60, v60, v59
	v_mov_b32_e32 v59, v62
	v_mov_b32_e32 v61, v63
	s_waitcnt vmcnt(1)
	v_pk_fma_f32 v[8:9], v[152:153], v[34:35], v[8:9]
	v_pk_add_f32 v[34:35], v[64:65], v[44:45]
	v_mov_b32_e32 v37, v48
	v_mov_b32_e32 v41, v49
	v_pk_add_f32 v[58:59], v[58:59], v[60:61]
	s_waitcnt vmcnt(0)
	v_pk_fma_f32 v[2:3], v[154:155], v[34:35], v[2:3]
	v_pk_add_f32 v[34:35], v[36:37], v[40:41]
	v_pk_fma_f32 v[6:7], v[150:151], v[58:59], v[6:7]
	v_pk_fma_f32 v[4:5], v[156:157], v[34:35], v[4:5]

.LBB0_426:
	s_andn2_b64 vcc, exec, s[12:13]
	s_cbranch_vccnz .LBB0_428
	v_or_b32_e32 v0, s14, v170
	v_lshlrev_b64 v[2:3], 10, v[0:1]
	v_lshl_or_b32 v2, s9, 7, v2
	s_lshl_b32 s12, s16, 4
	v_or_b32_e32 v2, s12, v2
	v_lshlrev_b64 v[2:3], 1, v[2:3]
	v_lshl_add_u64 v[4:5], s[30:31], 0, v[2:3]
	global_load_dwordx4 v[84:87], v[4:5], off offset:16
	global_load_dwordx4 v[92:95], v[4:5], off
	v_lshl_add_u64 v[10:11], s[42:43], 0, v[2:3]
	global_load_dwordx4 v[88:91], v[10:11], off offset:16
	global_load_dwordx4 v[96:99], v[10:11], off
	global_load_dwordx4 v[6:9], v[4:5], off offset:144
	global_load_dwordx4 v[80:83], v[4:5], off offset:128
	global_load_dwordx4 v[130:133], v[10:11], off offset:144
	global_load_dwordx4 v[134:137], v[10:11], off offset:128
	v_mov_b64_e32 v[2:3], s[74:75]
	v_mad_u64_u32 v[2:3], s[0:1], v0, s85, v[2:3]
	s_lshl_b32 s46, s9, 8
	v_lshl_add_u64 v[2:3], v[2:3], 0, s[46:47]
	s_lshl_b32 s46, s16, 5
	v_lshl_add_u64 v[100:101], v[2:3], 0, s[46:47]
	s_nop 0
	s_nop 0
	s_nop 0
	s_nop 0
	s_nop 0
	s_nop 0
	s_nop 0
	s_nop 0
	s_nop 0
	s_nop 0
	v_add_u32_e32 v0, s46, v179
	s_or_b32 s0, s12, 1
	s_mul_i32 s1, s0, 0x90
	s_add_i32 s12, s1, 0x90
	s_mulk_i32 s0, 0x88
	v_lshl_add_u64 v[14:15], v[100:101], 0, s[40:41]
	v_mov_b32_e32 v208, 0
	v_mov_b32_e32 v207, 0
	s_waitcnt vmcnt(6)
	ds_write2_b64 v0, v[92:93], v[94:95] offset1:1
	v_add_co_u32_e32 v92, vcc, s33, v100
	v_add_u32_e32 v0, 0x4200, v0
	s_nop 0
	v_addc_co_u32_e32 v93, vcc, 0, v101, vcc
	global_load_dwordx4 v[92:95], v[92:93], off
	global_load_dwordx4 v[140:143], v[14:15], off offset:16
	global_load_dwordx4 v[144:147], v[14:15], off offset:128
	global_load_dwordx4 v[100:103], v[14:15], off offset:144
	s_waitcnt vmcnt(8)
	ds_write2_b64 v0, v[96:97], v[98:99] offset1:1
	v_add_u32_e32 v0, s88, v189
	ds_write_b16 v0, v96 offset:33792
	v_add_u32_e32 v0, s1, v189
	ds_write_b16_d16_hi v0, v96 offset:33792
	v_add_u32_e32 v0, s12, v189
	s_add_i32 s12, s1, 0x120
	ds_write_b16 v0, v97 offset:33792
	v_add_u32_e32 v0, s12, v189
	s_add_i32 s12, s1, 0x1b0
	ds_write_b16_d16_hi v0, v97 offset:33792
	v_add_u32_e32 v0, s12, v189
	s_add_i32 s12, s1, 0x240
	ds_write_b16 v0, v98 offset:33792
	v_add_u32_e32 v0, s12, v189
	s_add_i32 s12, s1, 0x2d0
	ds_write_b16_d16_hi v0, v98 offset:33792
	v_add_u32_e32 v0, s12, v189
	s_addk_i32 s1, 0x360
	ds_write_b16 v0, v99 offset:33792
	v_add_u32_e32 v0, s1, v189
	ds_write_b16_d16_hi v0, v99 offset:33792
	v_add_u32_e32 v0, s17, v189
	s_add_i32 s1, s0, 0x88
	s_waitcnt vmcnt(3)
	ds_write_b16 v0, v92 offset:52224
	v_add_u32_e32 v0, s0, v189
	ds_write_b16_d16_hi v0, v92 offset:52224
	v_add_u32_e32 v0, s1, v189
	s_add_i32 s1, s0, 0x110
	ds_write_b16 v0, v93 offset:52224
	v_add_u32_e32 v0, s1, v189
	s_add_i32 s1, s0, 0x198
	ds_write_b16_d16_hi v0, v93 offset:52224
	v_add_u32_e32 v0, s1, v189
	s_add_i32 s1, s0, 0x220
	ds_write_b16 v0, v94 offset:52224
	v_add_u32_e32 v0, s1, v189
	s_add_i32 s1, s0, 0x2a8
	ds_write_b16_d16_hi v0, v94 offset:52224
	v_add_u32_e32 v0, s1, v189
	s_addk_i32 s0, 0x330
	ds_write_b16 v0, v95 offset:52224
	v_add_u32_e32 v0, s0, v189
	ds_write_b16_d16_hi v0, v95 offset:52224
	s_nop 0
	s_nop 0
	s_nop 0
	s_lshl_b32 s0, s16, 1
	s_or_b32 s1, s0, 1
	v_lshl_add_u32 v0, s1, 4, v179
	s_lshl_b32 s12, s1, 3
	ds_write2_b64 v0, v[84:85], v[86:87] offset1:1
	v_add_u32_e32 v0, 0x4200, v0
	s_mul_i32 s13, s1, 0x480
	s_or_b32 s12, s12, 1
	ds_write2_b64 v0, v[88:89], v[90:91] offset1:1
	v_add_u32_e32 v0, s13, v189
	s_mul_i32 s13, s12, 0x90
	ds_write_b16 v0, v88 offset:33792
	v_add_u32_e32 v0, s13, v189
	s_add_i32 s14, s13, 0x90
	ds_write_b16_d16_hi v0, v88 offset:33792
	v_add_u32_e32 v0, s14, v189
	s_add_i32 s14, s13, 0x120
	ds_write_b16 v0, v89 offset:33792
	v_add_u32_e32 v0, s14, v189
	s_add_i32 s14, s13, 0x1b0
	ds_write_b16_d16_hi v0, v89 offset:33792
	v_add_u32_e32 v0, s14, v189
	s_add_i32 s14, s13, 0x240
	ds_write_b16 v0, v90 offset:33792
	v_add_u32_e32 v0, s14, v189
	s_add_i32 s14, s13, 0x2d0
	ds_write_b16_d16_hi v0, v90 offset:33792
	v_add_u32_e32 v0, s14, v189
	s_addk_i32 s13, 0x360
	ds_write_b16 v0, v91 offset:33792
	v_add_u32_e32 v0, s13, v189
	s_mulk_i32 s1, 0x440
	ds_write_b16_d16_hi v0, v91 offset:33792
	v_add_u32_e32 v0, s1, v189
	s_mul_i32 s1, s12, 0x88
	s_add_i32 s12, s1, 0x88
	s_waitcnt vmcnt(2)
	ds_write_b16 v0, v140 offset:52224
	v_add_u32_e32 v0, s1, v189
	ds_write_b16_d16_hi v0, v140 offset:52224
	v_add_u32_e32 v0, s12, v189
	s_add_i32 s12, s1, 0x110
	ds_write_b16 v0, v141 offset:52224
	v_add_u32_e32 v0, s12, v189
	s_add_i32 s12, s1, 0x198
	ds_write_b16_d16_hi v0, v141 offset:52224
	v_add_u32_e32 v0, s12, v189
	s_add_i32 s12, s1, 0x220
	ds_write_b16 v0, v142 offset:52224
	v_add_u32_e32 v0, s12, v189
	s_add_i32 s12, s1, 0x2a8
	ds_write_b16_d16_hi v0, v142 offset:52224
	v_add_u32_e32 v0, s12, v189
	s_addk_i32 s1, 0x330
	ds_write_b16 v0, v143 offset:52224
	v_add_u32_e32 v0, s1, v189
	s_or_b32 s1, s0, 8
	ds_write_b16_d16_hi v0, v143 offset:52224
	v_lshl_add_u32 v0, s1, 4, v179
	s_lshl_b32 s12, s1, 3
	ds_write2_b64 v0, v[80:81], v[82:83] offset1:1
	v_add_u32_e32 v0, 0x4200, v0
	s_mul_i32 s13, s1, 0x480
	s_or_b32 s12, s12, 1
	ds_write2_b64 v0, v[134:135], v[136:137] offset1:1
	v_add_u32_e32 v0, s13, v189
	s_mul_i32 s13, s12, 0x90
	ds_write_b16 v0, v134 offset:33792
	v_add_u32_e32 v0, s13, v189
	s_add_i32 s14, s13, 0x90
	ds_write_b16_d16_hi v0, v134 offset:33792
	v_add_u32_e32 v0, s14, v189
	s_add_i32 s14, s13, 0x120
	ds_write_b16 v0, v135 offset:33792
	v_add_u32_e32 v0, s14, v189
	s_add_i32 s14, s13, 0x1b0
	ds_write_b16_d16_hi v0, v135 offset:33792
	v_add_u32_e32 v0, s14, v189
	s_add_i32 s14, s13, 0x240
	ds_write_b16 v0, v136 offset:33792
	v_add_u32_e32 v0, s14, v189
	s_add_i32 s14, s13, 0x2d0
	ds_write_b16_d16_hi v0, v136 offset:33792
	v_add_u32_e32 v0, s14, v189
	s_addk_i32 s13, 0x360
	ds_write_b16 v0, v137 offset:33792
	v_add_u32_e32 v0, s13, v189
	s_mulk_i32 s1, 0x440
	ds_write_b16_d16_hi v0, v137 offset:33792
	v_add_u32_e32 v0, s1, v189
	s_mul_i32 s1, s12, 0x88
	s_waitcnt vmcnt(1)
	ds_write_b16 v0, v144 offset:52224
	v_add_u32_e32 v0, s1, v189
	s_add_i32 s12, s1, 0x88
	ds_write_b16_d16_hi v0, v144 offset:52224
	v_add_u32_e32 v0, s12, v189
	s_add_i32 s12, s1, 0x110
	ds_write_b16 v0, v145 offset:52224
	v_add_u32_e32 v0, s12, v189
	s_add_i32 s12, s1, 0x198
	ds_write_b16_d16_hi v0, v145 offset:52224
	v_add_u32_e32 v0, s12, v189
	s_add_i32 s12, s1, 0x220
	ds_write_b16 v0, v146 offset:52224
	v_add_u32_e32 v0, s12, v189
	s_add_i32 s12, s1, 0x2a8
	ds_write_b16_d16_hi v0, v146 offset:52224
	v_add_u32_e32 v0, s12, v189
	s_addk_i32 s1, 0x330
	ds_write_b16 v0, v147 offset:52224
	v_add_u32_e32 v0, s1, v189
	s_or_b32 s0, s0, 9
	ds_write_b16_d16_hi v0, v147 offset:52224
	v_lshl_add_u32 v0, s0, 4, v179
	s_lshl_b32 s1, s0, 3
	ds_write2_b64 v0, v[6:7], v[8:9] offset1:1
	v_add_u32_e32 v0, 0x4200, v0
	s_mul_i32 s12, s0, 0x480
	s_or_b32 s1, s1, 1
	ds_write2_b64 v0, v[130:131], v[132:133] offset1:1
	v_add_u32_e32 v0, s12, v189
	s_mul_i32 s12, s1, 0x90
	ds_write_b16 v0, v130 offset:33792
	v_add_u32_e32 v0, s12, v189
	s_add_i32 s13, s12, 0x90
	ds_write_b16_d16_hi v0, v130 offset:33792
	v_add_u32_e32 v0, s13, v189
	s_add_i32 s13, s12, 0x120
	ds_write_b16 v0, v131 offset:33792
	v_add_u32_e32 v0, s13, v189
	s_add_i32 s13, s12, 0x1b0
	ds_write_b16_d16_hi v0, v131 offset:33792
	v_add_u32_e32 v0, s13, v189
	s_add_i32 s13, s12, 0x240
	ds_write_b16 v0, v132 offset:33792
	v_add_u32_e32 v0, s13, v189
	s_add_i32 s13, s12, 0x2d0
	ds_write_b16_d16_hi v0, v132 offset:33792
	v_add_u32_e32 v0, s13, v189
	s_addk_i32 s12, 0x360
	ds_write_b16 v0, v133 offset:33792
	v_add_u32_e32 v0, s12, v189
	s_mulk_i32 s0, 0x440
	ds_write_b16_d16_hi v0, v133 offset:33792
	v_add_u32_e32 v0, s0, v189
	s_mul_i32 s0, s1, 0x88
	s_waitcnt vmcnt(0)
	ds_write_b16 v0, v100 offset:52224
	v_add_u32_e32 v0, s0, v189
	s_add_i32 s1, s0, 0x88
	ds_write_b16_d16_hi v0, v100 offset:52224
	v_add_u32_e32 v0, s1, v189
	s_add_i32 s1, s0, 0x110
	ds_write_b16 v0, v101 offset:52224
	v_add_u32_e32 v0, s1, v189
	s_add_i32 s1, s0, 0x198
	ds_write_b16_d16_hi v0, v101 offset:52224
	v_add_u32_e32 v0, s1, v189
	s_add_i32 s1, s0, 0x220
	ds_write_b16 v0, v102 offset:52224
	v_add_u32_e32 v0, s1, v189
	s_add_i32 s1, s0, 0x2a8
	ds_write_b16_d16_hi v0, v102 offset:52224
	v_add_u32_e32 v0, s1, v189
	s_addk_i32 s0, 0x330
	ds_write_b16 v0, v103 offset:52224
	v_add_u32_e32 v0, s0, v189
	ds_write_b16_d16_hi v0, v103 offset:52224
	v_mov_b32_e32 v3, v131
	v_mov_b32_e32 v11, v135
	v_mov_b32_e32 v12, v136
	v_mov_b32_e32 v13, v137
	v_mov_b32_e32 v98, v146
	v_mov_b32_e32 v99, v147

.LBB0_430:
	s_not_b32 s8, s0
	s_add_i32 s12, s68, s8
	s_and_b64 s[8:9], s[10:11], exec
	s_cselect_b32 s8, s0, s12
	s_waitcnt lgkmcnt(0)
	s_barrier
	s_lshl_b32 s8, s8, 6
	s_add_i32 s8, s8, s69
	s_and_b64 vcc, exec, s[54:55]
	s_cbranch_vccz .LBB0_445
	v_or_b32_e32 v2, s8, v170
	v_ashrrev_i32_e32 v3, 31, v2
	v_lshlrev_b64 v[4:5], 11, v[2:3]
	s_lshl_b64 s[12:13], s[38:39], 1
	v_or_b32_e32 v5, s13, v5
	v_or_b32_e32 v4, s12, v4
	v_lshl_add_u64 v[12:13], s[30:31], 0, v[4:5]
	global_load_dwordx4 v[104:107], v[12:13], off offset:16
	global_load_dwordx4 v[8:11], v[12:13], off
	v_lshl_add_u64 v[84:85], s[42:43], 0, v[4:5]
	global_load_dwordx4 v[100:103], v[84:85], off offset:16
	global_load_dwordx4 v[80:83], v[84:85], off
	global_load_dwordx4 v[88:91], v[12:13], off offset:144
	global_load_dwordx4 v[96:99], v[12:13], off offset:128
	global_load_dwordx4 v[130:133], v[84:85], off offset:144
	global_load_dwordx4 v[92:95], v[84:85], off offset:128
	v_mov_b64_e32 v[4:5], s[74:75]
	v_mad_i64_i32 v[2:3], s[12:13], v2, s85, v[4:5]
	s_lshl_b32 s46, s83, 1
	v_lshl_add_u64 v[2:3], v[2:3], 0, s[46:47]
	s_lshl_b32 s46, s29, 1
	v_lshl_add_u64 v[86:87], v[2:3], 0, s[46:47]
	s_nop 0
	s_nop 0
	s_nop 0
	s_nop 0
	s_nop 0
	s_nop 0
	s_nop 0
	s_nop 0
	v_or_b32_e32 v12, s8, v206
	v_ashrrev_i32_e32 v13, 31, v12
	v_lshlrev_b64 v[12:13], 5, v[12:13]
	v_lshl_add_u64 v[84:85], s[56:57], 0, v[12:13]
	global_load_dword v0, v[84:85], off
	v_lshl_add_u64 v[12:13], s[2:3], 0, v[12:13]
	global_load_dword v108, v[12:13], off
	s_nop 0
	s_nop 0
	v_add_u32_e32 v12, s1, v209
	v_lshl_add_u64 v[6:7], v[86:87], 0, s[40:41]
	v_add_u32_e32 v109, s18, v209
	s_waitcnt vmcnt(8)
	ds_write2_b64 v12, v[8:9], v[10:11] offset1:1
	v_add_u32_e32 v8, 0x4200, v12
	s_waitcnt vmcnt(6)
	ds_write2_b64 v8, v[80:81], v[82:83] offset1:1
	v_add_u32_e32 v8, s88, v210
	ds_write_b16 v8, v80 offset:33792
	v_add_u32_e32 v8, s27, v210
	ds_write_b16_d16_hi v8, v80 offset:33792
	ds_write_b16 v8, v81 offset:33936
	ds_write_b16_d16_hi v8, v81 offset:34080
	ds_write_b16 v8, v82 offset:34224
	ds_write_b16_d16_hi v8, v82 offset:34368
	ds_write_b16 v8, v83 offset:34512
	ds_write_b16_d16_hi v8, v83 offset:34656
	v_add_co_u32_e32 v8, vcc, s33, v86
	s_nop 1
	v_addc_co_u32_e32 v9, vcc, 0, v87, vcc
	global_load_dwordx4 v[84:87], v[8:9], off
	global_load_dwordx4 v[80:83], v[6:7], off offset:16
	global_load_dwordx4 v[10:13], v[6:7], off offset:128
	global_load_dwordx4 v[134:137], v[6:7], off offset:144
	s_nop 0
	s_nop 0
	s_nop 0
	s_nop 0
	ds_write2_b64 v109, v[104:105], v[106:107] offset1:1
	v_add_u32_e32 v104, 0x4200, v109
	ds_write2_b64 v104, v[100:101], v[102:103] offset1:1
	v_add_u32_e32 v104, s19, v210
	v_add_u32_e32 v105, s64, v210
	ds_write_b16 v104, v100 offset:33792
	ds_write_b16_d16_hi v105, v100 offset:33792
	ds_write_b16 v105, v101 offset:33936
	ds_write_b16_d16_hi v105, v101 offset:34080
	ds_write_b16 v105, v102 offset:34224
	ds_write_b16_d16_hi v105, v102 offset:34368
	ds_write_b16 v105, v103 offset:34512
	ds_write_b16_d16_hi v105, v103 offset:34656
	v_add_u32_e32 v100, s90, v209
	s_waitcnt vmcnt(8)
	ds_write2_b64 v100, v[96:97], v[98:99] offset1:1
	v_add_u32_e32 v96, 0x4200, v100
	s_waitcnt vmcnt(6)
	ds_write2_b64 v96, v[92:93], v[94:95] offset1:1
	ds_write_b16 v104, v92 offset:41856
	v_add_u32_e32 v96, s91, v210
	ds_write_b16_d16_hi v96, v92 offset:33792
	ds_write_b16 v96, v93 offset:33936
	ds_write_b16_d16_hi v96, v93 offset:34080
	ds_write_b16 v96, v94 offset:34224
	ds_write_b16_d16_hi v96, v94 offset:34368
	ds_write_b16 v96, v95 offset:34512
	ds_write_b16_d16_hi v96, v95 offset:34656
	v_add_u32_e32 v92, s67, v209
	ds_write2_b64 v92, v[88:89], v[90:91] offset1:1
	v_add_u32_e32 v88, 0x4200, v92
	ds_write2_b64 v88, v[130:131], v[132:133] offset1:1
	ds_write_b16 v104, v130 offset:43008
	v_add_u32_e32 v88, s24, v210
	ds_write_b16_d16_hi v88, v130 offset:33792
	ds_write_b16 v88, v131 offset:33936
	ds_write_b16_d16_hi v88, v131 offset:34080
	ds_write_b16 v88, v132 offset:34224
	ds_write_b16_d16_hi v88, v132 offset:34368
	ds_write_b16 v88, v133 offset:34512
	ds_write_b16_d16_hi v88, v133 offset:34656
	s_waitcnt vmcnt(4)
	v_add_f32_dpp v130, v108, v108 row_shr:1 row_mask:0xf bank_mask:0xf bound_ctrl:1
	v_mov_b32_e32 v3, v1
	v_mov_b32_e32 v4, 0xff61b1e6
	v_add_f32_dpp v130, v130, v130 row_shr:2 row_mask:0xf bank_mask:0xf bound_ctrl:1
	s_nop 1
	v_add_f32_dpp v130, v130, v130 row_shr:4 row_mask:0xf bank_mask:0xf bound_ctrl:1
	s_nop 1
	v_add_f32_dpp v130, v130, v130 row_shr:8 row_mask:0xf bank_mask:0xf bound_ctrl:1
	s_nop 1
	v_mov_b32_dpp v3, v130 row_bcast:15 row_mask:0xa bank_mask:0xf
	v_add_f32_e32 v130, v130, v3
	v_mov_b32_e32 v3, v1
	s_nop 1
	v_mov_b32_dpp v3, v130 row_bcast:31 row_mask:0xc bank_mask:0xf
	v_add_f32_e32 v130, v130, v3
	v_sub_f32_e32 v0, v0, v130
	v_mov_b32_e32 v3, 0xff61b1e6
	s_nop 1
	v_mov_b32_dpp v3, v0 row_shr:1 row_mask:0xf bank_mask:0xf
	v_max_f32_e32 v3, v0, v3
	s_nop 1
	v_mov_b32_dpp v4, v3 row_shr:2 row_mask:0xf bank_mask:0xf
	v_max_f32_e32 v3, v3, v4
	v_mov_b32_e32 v4, 0xff61b1e6
	s_nop 1
	v_mov_b32_dpp v4, v3 row_shr:4 row_mask:0xf bank_mask:0xf
	v_max_f32_e32 v3, v3, v4
	v_mov_b32_e32 v4, 0xff61b1e6
	s_nop 1
	v_mov_b32_dpp v4, v3 row_shr:8 row_mask:0xf bank_mask:0xf
	v_max_f32_e32 v3, v3, v4
	v_mov_b32_e32 v4, 0xff61b1e6
	s_nop 1
	v_mov_b32_dpp v4, v3 row_bcast:15 row_mask:0xa bank_mask:0xf
	v_max_f32_e32 v3, v3, v4
	v_mov_b32_e32 v4, 0xff61b1e6
	s_nop 1
	v_mov_b32_dpp v4, v3 row_bcast:31 row_mask:0xc bank_mask:0xf
	v_max3_f32 v3, v217, v3, v4
	s_nop 0
	v_readlane_b32 s9, v3, 63
	s_nop 1
	v_subrev_f32_e32 v4, s9, v0
	v_mul_f32_e32 v4, 0x3fb8aa3b, v4
	v_exp_f32_e32 v4, v4
	ds_write2st64_b32 v211, v0, v3 offset1:1
	ds_write2st64_b32 v211, v130, v4 offset0:2 offset1:3
	v_add_u32_e32 v0, s17, v210
	s_waitcnt vmcnt(3)
	ds_write_b16 v0, v84 offset:52224
	v_add_u32_e32 v0, s78, v210
	ds_write_b16_d16_hi v0, v84 offset:52224
	ds_write_b16 v0, v85 offset:52360
	ds_write_b16_d16_hi v0, v85 offset:52496
	ds_write_b16 v0, v86 offset:52632
	ds_write_b16_d16_hi v0, v86 offset:52768
	ds_write_b16 v0, v87 offset:52904
	ds_write_b16_d16_hi v0, v87 offset:53040
	v_add_u32_e32 v0, s79, v210
	v_add_u32_e32 v2, s65, v210
	s_waitcnt vmcnt(2)
	ds_write_b16 v0, v80 offset:52224
	ds_write_b16_d16_hi v2, v80 offset:52224
	ds_write_b16 v2, v81 offset:52360
	ds_write_b16_d16_hi v2, v81 offset:52496
	ds_write_b16 v2, v82 offset:52632
	ds_write_b16_d16_hi v2, v82 offset:52768
	ds_write_b16 v2, v83 offset:52904
	ds_write_b16_d16_hi v2, v83 offset:53040
	s_waitcnt vmcnt(1)
	ds_write_b16 v0, v10 offset:59840
	v_add_u32_e32 v2, s66, v210
	ds_write_b16_d16_hi v2, v10 offset:52224
	ds_write_b16 v2, v11 offset:52360
	ds_write_b16_d16_hi v2, v11 offset:52496
	ds_write_b16 v2, v12 offset:52632
	ds_write_b16_d16_hi v2, v12 offset:52768
	ds_write_b16 v2, v13 offset:52904
	ds_write_b16_d16_hi v2, v13 offset:53040
	s_waitcnt vmcnt(0)
	ds_write_b16 v0, v134 offset:60928
	v_add_u32_e32 v0, s25, v210
	ds_write_b16_d16_hi v0, v134 offset:52224
	ds_write_b16 v0, v135 offset:52360
	ds_write_b16_d16_hi v0, v135 offset:52496
	ds_write_b16 v0, v136 offset:52632
	ds_write_b16_d16_hi v0, v136 offset:52768
	ds_write_b16 v0, v137 offset:52904
	ds_write_b16_d16_hi v0, v137 offset:53040
	s_waitcnt lgkmcnt(0)
	s_barrier
	s_mov_b64 s[12:13], -1
	s_cbranch_execz .LBB0_446
	s_mov_b32 s46, s28
	s_and_b64 vcc, exec, s[12:13]
	s_cbranch_vccz .LBB0_455

.LBB0_446:
	s_sub_i32 s14, s26, s0
	s_add_i32 s9, s0, 1
	s_and_b64 s[12:13], s[10:11], exec
	s_cselect_b32 s12, s9, s14
	s_lshl_b32 s20, s12, 6
	s_add_i32 s20, s20, s69
	s_cmp_lt_u32 s9, s68
	s_cselect_b64 s[12:13], -1, 0
	v_cndmask_b32_e64 v0, 0, 1, s[12:13]
	s_mov_b64 s[14:15], -1
	s_andn2_b64 vcc, exec, s[36:37]
	v_cmp_ne_u32_e64 s[12:13], 1, v0
	s_cbranch_vccnz .LBB0_450
	s_and_b64 vcc, exec, s[12:13]
	s_cbranch_vccnz .LBB0_449
	s_bitcmp1_b32 s9, 0
	v_or_b32_e32 v2, s20, v170
	s_cselect_b32 s14, 0x11000, 0
	v_ashrrev_i32_e32 v3, 31, v2
	s_add_i32 s21, s14, 0
	v_lshlrev_b64 v[4:5], 11, v[2:3]
	s_lshl_b64 s[14:15], s[38:39], 1
	v_or_b32_e32 v5, s15, v5
	v_or_b32_e32 v4, s14, v4
	v_lshl_add_u64 v[10:11], s[30:31], 0, v[4:5]
	global_load_dwordx4 v[96:99], v[10:11], off offset:16
	global_load_dwordx4 v[84:87], v[10:11], off
	v_lshl_add_u64 v[12:13], s[42:43], 0, v[4:5]
	global_load_dwordx4 v[88:91], v[12:13], off offset:16
	global_load_dwordx4 v[102:105], v[12:13], off
	global_load_dwordx4 v[6:9], v[10:11], off offset:144
	global_load_dwordx4 v[80:83], v[10:11], off offset:128
	global_load_dwordx4 v[130:133], v[12:13], off offset:144
	global_load_dwordx4 v[134:137], v[12:13], off offset:128
	v_mov_b64_e32 v[4:5], s[74:75]
	v_mad_i64_i32 v[2:3], s[14:15], v2, s85, v[4:5]
	s_lshl_b32 s46, s83, 1
	v_lshl_add_u64 v[2:3], v[2:3], 0, s[46:47]
	s_lshl_b32 s46, s29, 1
	v_lshl_add_u64 v[94:95], v[2:3], 0, s[46:47]
	s_nop 0
	s_nop 0
	s_nop 0
	s_nop 0
	s_nop 0
	s_nop 0
	s_nop 0
	s_nop 0
	s_nop 0
	v_add_u32_e32 v100, s21, v175
	v_add_u32_e32 v0, s1, v100
	v_lshl_add_u64 v[92:93], v[94:95], 0, s[40:41]
	s_waitcnt vmcnt(6)
	ds_write2_b64 v0, v[84:85], v[86:87] offset1:1
	v_add_u32_e32 v0, 0x4200, v0
	s_waitcnt vmcnt(4)
	ds_write2_b64 v0, v[102:103], v[104:105] offset1:1
	v_add_u32_e32 v0, s21, v188
	v_add_u32_e32 v84, s88, v0
	ds_write_b16 v84, v102 offset:33792
	v_add_u32_e32 v84, s27, v0
	ds_write_b16_d16_hi v84, v102 offset:33792
	ds_write_b16 v84, v103 offset:33936
	ds_write_b16_d16_hi v84, v103 offset:34080
	ds_write_b16 v84, v104 offset:34224
	ds_write_b16_d16_hi v84, v104 offset:34368
	ds_write_b16 v84, v105 offset:34512
	ds_write_b16_d16_hi v84, v105 offset:34656
	v_add_co_u32_e32 v84, vcc, s33, v94
	v_add_u32_e32 v101, s17, v0
	s_nop 0
	v_addc_co_u32_e32 v85, vcc, 0, v95, vcc
	global_load_dwordx4 v[84:87], v[84:85], off
	global_load_dwordx4 v[102:105], v[92:93], off offset:16
	global_load_dwordx4 v[140:143], v[92:93], off offset:128
	global_load_dwordx4 v[144:147], v[92:93], off offset:144
	v_add_u32_e32 v94, s78, v0
	s_waitcnt vmcnt(3)
	ds_write_b16 v101, v84 offset:52224
	ds_write_b16_d16_hi v94, v84 offset:52224
	ds_write_b16 v94, v85 offset:52360
	ds_write_b16_d16_hi v94, v85 offset:52496
	ds_write_b16 v94, v86 offset:52632
	ds_write_b16_d16_hi v94, v86 offset:52768
	ds_write_b16 v94, v87 offset:52904
	ds_write_b16_d16_hi v94, v87 offset:53040
	s_nop 0
	s_nop 0
	s_nop 0
	s_nop 0
	v_add_u32_e32 v101, s18, v100
	ds_write2_b64 v101, v[96:97], v[98:99] offset1:1
	v_add_u32_e32 v96, 0x4200, v101
	ds_write2_b64 v96, v[88:89], v[90:91] offset1:1
	v_add_u32_e32 v96, s19, v0
	v_add_u32_e32 v97, s64, v0
	ds_write_b16 v96, v88 offset:33792
	ds_write_b16_d16_hi v97, v88 offset:33792
	ds_write_b16 v97, v89 offset:33936
	ds_write_b16_d16_hi v97, v89 offset:34080
	ds_write_b16 v97, v90 offset:34224
	ds_write_b16_d16_hi v97, v90 offset:34368
	ds_write_b16 v97, v91 offset:34512
	ds_write_b16_d16_hi v97, v91 offset:34656
	v_add_u32_e32 v88, s79, v0
	v_add_u32_e32 v89, s65, v0
	s_waitcnt vmcnt(2)
	ds_write_b16 v88, v102 offset:52224
	ds_write_b16_d16_hi v89, v102 offset:52224
	ds_write_b16 v89, v103 offset:52360
	ds_write_b16_d16_hi v89, v103 offset:52496
	ds_write_b16 v89, v104 offset:52632
	ds_write_b16_d16_hi v89, v104 offset:52768
	ds_write_b16 v89, v105 offset:52904
	ds_write_b16_d16_hi v89, v105 offset:53040
	v_add_u32_e32 v89, s90, v100
	ds_write2_b64 v89, v[80:81], v[82:83] offset1:1
	v_add_u32_e32 v80, 0x4200, v89
	ds_write2_b64 v80, v[134:135], v[136:137] offset1:1
	ds_write_b16 v96, v134 offset:41856
	v_add_u32_e32 v80, s91, v0
	ds_write_b16_d16_hi v80, v134 offset:33792
	ds_write_b16 v80, v135 offset:33936
	ds_write_b16_d16_hi v80, v135 offset:34080
	ds_write_b16 v80, v136 offset:34224
	ds_write_b16_d16_hi v80, v136 offset:34368
	ds_write_b16 v80, v137 offset:34512
	ds_write_b16_d16_hi v80, v137 offset:34656
	s_waitcnt vmcnt(1)
	ds_write_b16 v88, v140 offset:59840
	v_add_u32_e32 v10, s66, v0
	ds_write_b16_d16_hi v10, v140 offset:52224
	ds_write_b16 v10, v141 offset:52360
	ds_write_b16_d16_hi v10, v141 offset:52496
	ds_write_b16 v10, v142 offset:52632
	ds_write_b16_d16_hi v10, v142 offset:52768
	ds_write_b16 v10, v143 offset:52904
	ds_write_b16_d16_hi v10, v143 offset:53040
	v_add_u32_e32 v10, s67, v100
	ds_write2_b64 v10, v[6:7], v[8:9] offset1:1
	v_add_u32_e32 v6, 0x4200, v10
	ds_write2_b64 v6, v[130:131], v[132:133] offset1:1
	ds_write_b16 v96, v130 offset:43008
	v_add_u32_e32 v6, s24, v0
	v_add_u32_e32 v0, s25, v0
	ds_write_b16_d16_hi v6, v130 offset:33792
	ds_write_b16 v6, v131 offset:33936
	ds_write_b16_d16_hi v6, v131 offset:34080
	ds_write_b16 v6, v132 offset:34224
	ds_write_b16_d16_hi v6, v132 offset:34368
	ds_write_b16 v6, v133 offset:34512
	ds_write_b16_d16_hi v6, v133 offset:34656
	s_waitcnt vmcnt(0)
	ds_write_b16 v88, v144 offset:60928
	ds_write_b16_d16_hi v0, v144 offset:52224
	ds_write_b16 v0, v145 offset:52360
	ds_write_b16_d16_hi v0, v145 offset:52496
	ds_write_b16 v0, v146 offset:52632
	ds_write_b16_d16_hi v0, v146 offset:52768
	ds_write_b16 v0, v147 offset:52904
	ds_write_b16_d16_hi v0, v147 offset:53040
	v_mov_b32_e32 v3, v131
	v_mov_b32_e32 v11, v135
	v_mov_b32_e32 v12, v136
	v_mov_b32_e32 v13, v137

.LBB0_463:
	v_add_u32_e32 v56, s2, v70
	v_ashrrev_i32_e32 v57, 31, v56
	v_lshlrev_b64 v[2:3], 11, v[56:57]
	v_lshl_add_u64 v[2:3], s[62:63], 0, v[2:3]
	v_lshl_add_u64 v[2:3], v[2:3], 0, v[0:1]
	global_load_dwordx4 v[34:37], v[2:3], off
	v_add_co_u32_e32 v2, vcc, 0x1400000, v2
	v_mov_b64_e32 v[10:11], s[74:75]
	s_nop 0
	v_addc_co_u32_e32 v3, vcc, 0, v3, vcc
	global_load_dwordx4 v[38:41], v[2:3], off
	v_mad_i64_i32 v[2:3], s[2:3], v56, s85, v[10:11]
	v_lshl_add_u64 v[2:3], v[2:3], 0, v[0:1]
	v_add_co_u32_e32 v2, vcc, s4, v2
	v_add_u32_e32 v54, 32, v56
	s_nop 0
	v_addc_co_u32_e32 v3, vcc, 0, v3, vcc
	global_load_dwordx4 v[58:61], v[2:3], off offset:2048
	v_ashrrev_i32_e32 v55, 31, v54
	v_lshlrev_b64 v[2:3], 11, v[54:55]
	v_lshl_add_u64 v[2:3], s[62:63], 0, v[2:3]
	v_lshl_add_u64 v[2:3], v[2:3], 0, v[0:1]
	global_load_dwordx4 v[26:29], v[2:3], off
	v_add_co_u32_e32 v2, vcc, s5, v2
	v_add_u32_e32 v52, 64, v56
	s_nop 0
	v_addc_co_u32_e32 v3, vcc, 0, v3, vcc
	global_load_dwordx4 v[30:33], v[2:3], off
	v_mad_i64_i32 v[2:3], s[2:3], v54, s85, v[10:11]
	v_lshl_add_u64 v[2:3], v[2:3], 0, v[0:1]
	v_add_co_u32_e32 v2, vcc, s4, v2
	v_ashrrev_i32_e32 v53, 31, v52
	s_nop 0
	v_addc_co_u32_e32 v3, vcc, 0, v3, vcc
	global_load_dwordx4 v[42:45], v[2:3], off offset:2048
	v_lshlrev_b64 v[2:3], 11, v[52:53]
	v_lshl_add_u64 v[2:3], s[62:63], 0, v[2:3]
	v_lshl_add_u64 v[2:3], v[2:3], 0, v[0:1]
	global_load_dwordx4 v[14:17], v[2:3], off
	v_add_co_u32_e32 v2, vcc, s5, v2
	v_add_u32_e32 v50, 0x60, v56
	s_nop 0
	v_addc_co_u32_e32 v3, vcc, 0, v3, vcc
	global_load_dwordx4 v[18:21], v[2:3], off
	v_mad_i64_i32 v[2:3], s[2:3], v52, s85, v[10:11]
	v_lshl_add_u64 v[2:3], v[2:3], 0, v[0:1]
	v_add_co_u32_e32 v2, vcc, s4, v2
	v_ashrrev_i32_e32 v51, 31, v50
	s_nop 0
	v_addc_co_u32_e32 v3, vcc, 0, v3, vcc
	global_load_dwordx4 v[22:25], v[2:3], off offset:2048
	v_lshlrev_b64 v[2:3], 11, v[50:51]
	v_lshl_add_u64 v[2:3], s[62:63], 0, v[2:3]
	v_lshl_add_u64 v[6:7], v[2:3], 0, v[0:1]
	global_load_dwordx4 v[2:5], v[6:7], off
	v_add_co_u32_e32 v6, vcc, s5, v6
	v_mad_i64_i32 v[10:11], s[2:3], v50, s85, v[10:11]
	s_nop 0
	v_addc_co_u32_e32 v7, vcc, 0, v7, vcc
	global_load_dwordx4 v[6:9], v[6:7], off
	v_lshl_add_u64 v[10:11], v[10:11], 0, v[0:1]
	v_add_co_u32_e32 v10, vcc, s4, v10
	s_nop 0
	s_nop 0
	v_addc_co_u32_e32 v11, vcc, 0, v11, vcc
	global_load_dwordx4 v[10:13], v[10:11], off offset:2048
	s_movk_i32 s2, 0x80
	s_and_b64 vcc, exec, s[0:1]
	global_load_dwordx4 v[88:91], v[48:49], off offset:16
	global_load_dwordx4 v[76:79], v[48:49], off
	s_mov_b64 s[0:1], 0
	s_waitcnt vmcnt(13)
	v_lshlrev_b32_e32 v72, 16, v36
	v_and_b32_e32 v73, 0xffff0000, v36
	v_lshlrev_b32_e32 v80, 16, v35
	v_and_b32_e32 v81, 0xffff0000, v35
	v_lshlrev_b32_e32 v84, 16, v34
	v_and_b32_e32 v85, 0xffff0000, v34
	s_waitcnt vmcnt(12)
	v_lshlrev_b32_e32 v36, 16, v40
	v_lshlrev_b32_e32 v34, 16, v38
	v_and_b32_e32 v35, 0xffff0000, v38
	v_lshlrev_b32_e32 v82, 16, v39
	v_and_b32_e32 v83, 0xffff0000, v39
	v_pk_add_f32 v[34:35], v[84:85], v[34:35]
	v_pk_add_f32 v[80:81], v[80:81], v[82:83]
	v_pk_mul_f32 v[38:39], v[34:35], v[34:35]
	v_pk_mul_f32 v[82:83], v[80:81], v[80:81]
	s_waitcnt vmcnt(11)
	v_lshlrev_b32_e32 v62, 16, v58
	v_and_b32_e32 v63, 0xffff0000, v58
	v_lshlrev_b32_e32 v66, 16, v60
	v_and_b32_e32 v67, 0xffff0000, v60
	v_lshlrev_b32_e32 v64, 16, v59
	v_and_b32_e32 v65, 0xffff0000, v59
	v_mul_f32_e32 v58, 0xbfb8aa3b, v62
	v_mul_f32_e32 v59, 0xbfb8aa3b, v63
	v_mul_f32_e32 v62, 0xbfb8aa3b, v66
	v_mul_f32_e32 v63, 0xbfb8aa3b, v67
	v_lshlrev_b32_e32 v66, 16, v37
	v_and_b32_e32 v67, 0xffff0000, v37
	v_and_b32_e32 v37, 0xffff0000, v40
	v_pk_add_f32 v[36:37], v[72:73], v[36:37]
	s_nop 0
	s_nop 0
	v_add_f32_e32 v38, v38, v39
	v_lshlrev_b32_e32 v68, 16, v61
	v_and_b32_e32 v69, 0xffff0000, v61
	v_add_f32_e32 v38, v82, v38
	v_mul_f32_e32 v60, 0xbfb8aa3b, v64
	v_mul_f32_e32 v61, 0xbfb8aa3b, v65
	v_mul_f32_e32 v64, 0xbfb8aa3b, v68
	v_mul_f32_e32 v65, 0xbfb8aa3b, v69
	v_lshlrev_b32_e32 v68, 16, v41
	v_and_b32_e32 v69, 0xffff0000, v41
	v_pk_mul_f32 v[40:41], v[36:37], v[36:37]
	v_add_f32_e32 v38, v83, v38
	v_pk_add_f32 v[66:67], v[66:67], v[68:69]
	v_add_f32_e32 v38, v40, v38
	v_pk_mul_f32 v[68:69], v[66:67], v[66:67]
	v_add_f32_e32 v38, v41, v38
	v_add_f32_e32 v38, v68, v38
	v_add_f32_e32 v38, v69, v38
	v_exp_f32_e32 v62, v62
	v_exp_f32_e32 v63, v63
	v_add_f32_dpp v38, v38, v38 quad_perm:[1,0,3,2] row_mask:0xf bank_mask:0xf bound_ctrl:1
	v_exp_f32_e32 v64, v64
	v_exp_f32_e32 v65, v65
	v_add_f32_dpp v38, v38, v38 quad_perm:[2,3,0,1] row_mask:0xf bank_mask:0xf bound_ctrl:1
	v_exp_f32_e32 v58, v58
	v_exp_f32_e32 v59, v59
	v_add_f32_dpp v38, v38, v38 row_half_mirror row_mask:0xf bank_mask:0xf bound_ctrl:1
	v_exp_f32_e32 v60, v60
	v_exp_f32_e32 v61, v61
	v_add_f32_dpp v38, v38, v38 row_mirror row_mask:0xf bank_mask:0xf bound_ctrl:1
	v_fmamk_f32 v38, v38, 0x3c000000, v233
	v_rsq_f32_e32 v38, v38
	v_add_f32_e32 v62, 1.0, v62
	v_add_f32_e32 v63, 1.0, v63
	v_add_f32_e32 v64, 1.0, v64
	v_add_f32_e32 v65, 1.0, v65
	v_add_f32_e32 v58, 1.0, v58
	v_add_f32_e32 v59, 1.0, v59
	v_add_f32_e32 v60, 1.0, v60
	v_add_f32_e32 v61, 1.0, v61
	v_rcp_f32_e32 v62, v62
	v_rcp_f32_e32 v63, v63
	v_rcp_f32_e32 v64, v64
	v_rcp_f32_e32 v65, v65
	v_rcp_f32_e32 v58, v58
	v_rcp_f32_e32 v59, v59
	v_rcp_f32_e32 v60, v60
	v_rcp_f32_e32 v61, v61
	v_pk_mul_f32 v[34:35], v[34:35], v[38:39] op_sel_hi:[1,0]
	v_pk_mul_f32 v[40:41], v[80:81], v[38:39] op_sel_hi:[1,0]
	v_pk_mul_f32 v[36:37], v[36:37], v[38:39] op_sel_hi:[1,0]
	v_pk_mul_f32 v[38:39], v[66:67], v[38:39] op_sel_hi:[1,0]
	s_waitcnt vmcnt(10)
	v_lshlrev_b32_e32 v68, 16, v26
	v_and_b32_e32 v69, 0xffff0000, v26
	s_waitcnt vmcnt(9)
	v_lshlrev_b32_e32 v26, 16, v30
	v_lshlrev_b32_e32 v66, 16, v31
	v_and_b32_e32 v67, 0xffff0000, v31
	s_waitcnt vmcnt(1)
	v_pk_mul_f32 v[36:37], v[88:89], v[36:37]
	v_pk_mul_f32 v[38:39], v[38:39], v[90:91]
	s_waitcnt vmcnt(0)
	v_pk_mul_f32 v[34:35], v[76:77], v[34:35]
	v_pk_mul_f32 v[40:41], v[78:79], v[40:41]
	v_pk_mul_f32 v[36:37], v[62:63], v[36:37]
	v_pk_mul_f32 v[38:39], v[64:65], v[38:39]
	v_pk_mul_f32 v[34:35], v[58:59], v[34:35]
	v_pk_mul_f32 v[40:41], v[60:61], v[40:41]
	v_cvt_pk_bf16_f32 v36, v36, v37
	v_cvt_pk_bf16_f32 v37, v38, v39
	v_lshlrev_b64 v[38:39], 12, v[56:57]
	v_cvt_pk_bf16_f32 v34, v34, v35
	v_cvt_pk_bf16_f32 v35, v40, v41
	v_lshl_add_u64 v[38:39], v[46:47], 0, v[38:39]
	global_store_dwordx4 v[38:39], v[34:37], off
	global_load_dwordx4 v[92:95], v[48:49], off offset:16
	global_load_dwordx4 v[132:135], v[48:49], off
	v_lshlrev_b32_e32 v38, 16, v44
	v_and_b32_e32 v39, 0xffff0000, v44
	v_lshlrev_b32_e32 v34, 16, v42
	v_mul_f32_e32 v34, 0xbfb8aa3b, v34
	v_exp_f32_e32 v34, v34
	v_and_b32_e32 v35, 0xffff0000, v42
	v_lshlrev_b32_e32 v36, 16, v43
	v_and_b32_e32 v37, 0xffff0000, v43
	v_add_f32_e32 v34, 1.0, v34
	v_rcp_f32_e32 v40, v34
	v_mul_f32_e32 v34, 0xbfb8aa3b, v35
	v_exp_f32_e32 v34, v34
	v_lshlrev_b32_e32 v56, 16, v45
	v_and_b32_e32 v57, 0xffff0000, v45
	v_and_b32_e32 v35, 0xffff0000, v29
	v_add_f32_e32 v34, 1.0, v34
	v_rcp_f32_e32 v41, v34
	v_mul_f32_e32 v34, 0xbfb8aa3b, v36
	v_exp_f32_e32 v34, v34
	v_lshlrev_b32_e32 v36, 16, v33
	v_lshlrev_b32_e32 v64, 16, v27
	v_and_b32_e32 v65, 0xffff0000, v27
	v_add_f32_e32 v34, 1.0, v34
	v_rcp_f32_e32 v42, v34
	v_mul_f32_e32 v34, 0xbfb8aa3b, v37
	v_exp_f32_e32 v34, v34
	v_and_b32_e32 v37, 0xffff0000, v33
	v_and_b32_e32 v27, 0xffff0000, v30
	v_pk_add_f32 v[26:27], v[68:69], v[26:27]
	v_add_f32_e32 v34, 1.0, v34
	v_rcp_f32_e32 v43, v34
	v_mul_f32_e32 v34, 0xbfb8aa3b, v38
	v_exp_f32_e32 v34, v34
	v_pk_add_f32 v[64:65], v[64:65], v[66:67]
	v_pk_mul_f32 v[30:31], v[26:27], v[26:27]
	v_pk_mul_f32 v[66:67], v[64:65], v[64:65]
	v_add_f32_e32 v34, 1.0, v34
	v_rcp_f32_e32 v44, v34
	v_mul_f32_e32 v34, 0xbfb8aa3b, v39
	v_exp_f32_e32 v34, v34
	v_add_f32_e32 v30, v30, v31
	v_add_f32_e32 v30, v66, v30
	v_add_f32_e32 v30, v67, v30
	v_add_f32_e32 v34, 1.0, v34
	v_rcp_f32_e32 v45, v34
	v_mul_f32_e32 v34, 0xbfb8aa3b, v56
	v_exp_f32_e32 v34, v34
	s_nop 0
	v_add_f32_e32 v34, 1.0, v34
	v_rcp_f32_e32 v56, v34
	v_mul_f32_e32 v34, 0xbfb8aa3b, v57
	v_exp_f32_e32 v34, v34
	s_nop 0
	v_add_f32_e32 v34, 1.0, v34
	v_rcp_f32_e32 v57, v34
	v_lshlrev_b32_e32 v34, 16, v29
	v_pk_add_f32 v[58:59], v[34:35], v[36:37]
	v_lshlrev_b32_e32 v34, 16, v28
	v_and_b32_e32 v35, 0xffff0000, v28
	v_lshlrev_b32_e32 v28, 16, v32
	v_and_b32_e32 v29, 0xffff0000, v32
	v_pk_add_f32 v[28:29], v[34:35], v[28:29]
	s_nop 0
	s_nop 0
	v_pk_mul_f32 v[62:63], v[28:29], v[28:29]
	v_pk_mul_f32 v[60:61], v[58:59], v[58:59]
	v_add_f32_e32 v30, v62, v30
	v_add_f32_e32 v30, v63, v30
	v_add_f32_e32 v30, v60, v30
	v_add_f32_e32 v30, v61, v30
	s_nop 1
	v_add_f32_dpp v30, v30, v30 quad_perm:[1,0,3,2] row_mask:0xf bank_mask:0xf bound_ctrl:1
	s_nop 1
	v_add_f32_dpp v30, v30, v30 quad_perm:[2,3,0,1] row_mask:0xf bank_mask:0xf bound_ctrl:1
	s_nop 1
	v_add_f32_dpp v30, v30, v30 row_half_mirror row_mask:0xf bank_mask:0xf bound_ctrl:1
	s_nop 1
	v_add_f32_dpp v30, v30, v30 row_mirror row_mask:0xf bank_mask:0xf bound_ctrl:1
	v_fmamk_f32 v30, v30, 0x3c000000, v233
	v_rsq_f32_e32 v30, v30
	s_nop 0
	v_pk_mul_f32 v[26:27], v[26:27], v[30:31] op_sel_hi:[1,0]
	v_pk_mul_f32 v[28:29], v[28:29], v[30:31] op_sel_hi:[1,0]
	s_waitcnt vmcnt(0)
	v_pk_mul_f32 v[26:27], v[132:133], v[26:27]
	v_pk_mul_f32 v[36:37], v[64:65], v[30:31] op_sel_hi:[1, 0]
	v_pk_mul_f32 v[30:31], v[58:59], v[30:31] op_sel_hi:[1,0]
	v_pk_mul_f32 v[28:29], v[92:93], v[28:29]
	v_pk_mul_f32 v[30:31], v[30:31], v[94:95]
	v_pk_mul_f32 v[36:37], v[134:135], v[36:37]
	v_pk_mul_f32 v[28:29], v[44:45], v[28:29]
	v_pk_mul_f32 v[30:31], v[56:57], v[30:31]
	v_pk_mul_f32 v[26:27], v[40:41], v[26:27]
	v_pk_mul_f32 v[36:37], v[42:43], v[36:37]
	v_cvt_pk_bf16_f32 v28, v28, v29
	v_cvt_pk_bf16_f32 v29, v30, v31
	v_lshlrev_b64 v[30:31], 12, v[54:55]
	v_cvt_pk_bf16_f32 v26, v26, v27
	v_cvt_pk_bf16_f32 v27, v36, v37
	v_lshl_add_u64 v[30:31], v[46:47], 0, v[30:31]
	global_store_dwordx4 v[30:31], v[26:29], off
	global_load_dwordx4 v[136:139], v[48:49], off offset:16
	global_load_dwordx4 v[140:143], v[48:49], off
	v_lshlrev_b32_e32 v32, 16, v24
	v_and_b32_e32 v24, 0xffff0000, v24
	v_lshlrev_b32_e32 v26, 16, v22
	v_and_b32_e32 v22, 0xffff0000, v22
	v_mul_f32_e32 v22, 0xbfb8aa3b, v22
	v_exp_f32_e32 v22, v22
	v_lshlrev_b32_e32 v27, 16, v23
	v_and_b32_e32 v23, 0xffff0000, v23
	v_lshlrev_b32_e32 v34, 16, v25
	v_add_f32_e32 v22, 1.0, v22
	v_rcp_f32_e32 v29, v22
	v_mul_f32_e32 v22, 0xbfb8aa3b, v27
	v_exp_f32_e32 v22, v22
	v_and_b32_e32 v25, 0xffff0000, v25
	v_mul_f32_e32 v26, 0xbfb8aa3b, v26
	v_exp_f32_e32 v26, v26
	v_add_f32_e32 v22, 1.0, v22
	v_rcp_f32_e32 v30, v22
	v_mul_f32_e32 v22, 0xbfb8aa3b, v23
	v_exp_f32_e32 v22, v22
	v_and_b32_e32 v23, 0xffff0000, v17
	v_add_f32_e32 v26, 1.0, v26
	v_rcp_f32_e32 v28, v26
	v_add_f32_e32 v22, 1.0, v22
	v_rcp_f32_e32 v31, v22
	v_mul_f32_e32 v22, 0xbfb8aa3b, v32
	v_exp_f32_e32 v22, v22
	v_lshlrev_b32_e32 v42, 16, v15
	v_and_b32_e32 v43, 0xffff0000, v15
	v_lshlrev_b32_e32 v54, 16, v14
	v_add_f32_e32 v22, 1.0, v22
	v_rcp_f32_e32 v32, v22
	v_mul_f32_e32 v22, 0xbfb8aa3b, v24
	v_exp_f32_e32 v22, v22
	v_lshlrev_b32_e32 v24, 16, v21
	v_and_b32_e32 v55, 0xffff0000, v14
	v_lshlrev_b32_e32 v14, 16, v18
	v_add_f32_e32 v22, 1.0, v22
	v_rcp_f32_e32 v33, v22
	v_mul_f32_e32 v22, 0xbfb8aa3b, v34
	v_exp_f32_e32 v22, v22
	v_and_b32_e32 v15, 0xffff0000, v18
	v_lshlrev_b32_e32 v44, 16, v19
	v_and_b32_e32 v45, 0xffff0000, v19
	v_add_f32_e32 v22, 1.0, v22
	v_rcp_f32_e32 v34, v22
	v_mul_f32_e32 v22, 0xbfb8aa3b, v25
	v_exp_f32_e32 v22, v22
	v_and_b32_e32 v25, 0xffff0000, v21
	v_pk_add_f32 v[14:15], v[54:55], v[14:15]
	v_pk_add_f32 v[42:43], v[42:43], v[44:45]
	v_add_f32_e32 v22, 1.0, v22
	v_rcp_f32_e32 v35, v22
	v_lshlrev_b32_e32 v22, 16, v17
	v_pk_add_f32 v[36:37], v[22:23], v[24:25]
	v_lshlrev_b32_e32 v22, 16, v16
	v_and_b32_e32 v23, 0xffff0000, v16
	v_lshlrev_b32_e32 v16, 16, v20
	v_and_b32_e32 v17, 0xffff0000, v20
	v_pk_add_f32 v[16:17], v[22:23], v[16:17]
	s_nop 0
	s_nop 0
	v_pk_mul_f32 v[18:19], v[14:15], v[14:15]
	v_pk_mul_f32 v[44:45], v[42:43], v[42:43]
	v_add_f32_e32 v18, v18, v19
	v_add_f32_e32 v18, v44, v18
	v_pk_mul_f32 v[40:41], v[16:17], v[16:17]
	v_add_f32_e32 v18, v45, v18
	v_add_f32_e32 v18, v40, v18
	v_pk_mul_f32 v[38:39], v[36:37], v[36:37]
	v_add_f32_e32 v18, v41, v18
	v_add_f32_e32 v18, v38, v18
	v_add_f32_e32 v18, v39, v18
	s_nop 1
	v_add_f32_dpp v18, v18, v18 quad_perm:[1,0,3,2] row_mask:0xf bank_mask:0xf bound_ctrl:1
	s_nop 1
	v_add_f32_dpp v18, v18, v18 quad_perm:[2,3,0,1] row_mask:0xf bank_mask:0xf bound_ctrl:1
	s_nop 1
	v_add_f32_dpp v18, v18, v18 row_half_mirror row_mask:0xf bank_mask:0xf bound_ctrl:1
	s_nop 1
	v_add_f32_dpp v18, v18, v18 row_mirror row_mask:0xf bank_mask:0xf bound_ctrl:1
	v_fmamk_f32 v18, v18, 0x3c000000, v233
	v_rsq_f32_e32 v18, v18
	s_nop 0
	v_pk_mul_f32 v[14:15], v[14:15], v[18:19] op_sel_hi:[1,0]
	v_pk_mul_f32 v[16:17], v[16:17], v[18:19] op_sel_hi:[1,0]
	s_waitcnt vmcnt(0)
	v_pk_mul_f32 v[14:15], v[140:141], v[14:15]
	v_pk_mul_f32 v[24:25], v[42:43], v[18:19] op_sel_hi:[1, 0]
	v_pk_mul_f32 v[18:19], v[36:37], v[18:19] op_sel_hi:[1,0]
	v_pk_mul_f32 v[16:17], v[136:137], v[16:17]
	v_pk_mul_f32 v[18:19], v[18:19], v[138:139]
	v_pk_mul_f32 v[24:25], v[142:143], v[24:25]
	v_pk_mul_f32 v[16:17], v[32:33], v[16:17]
	v_pk_mul_f32 v[18:19], v[34:35], v[18:19]
	v_pk_mul_f32 v[14:15], v[28:29], v[14:15]
	v_pk_mul_f32 v[24:25], v[30:31], v[24:25]
	v_cvt_pk_bf16_f32 v16, v16, v17
	v_cvt_pk_bf16_f32 v17, v18, v19
	v_lshlrev_b64 v[18:19], 12, v[52:53]
	v_cvt_pk_bf16_f32 v14, v14, v15
	v_cvt_pk_bf16_f32 v15, v24, v25
	v_lshl_add_u64 v[18:19], v[46:47], 0, v[18:19]
	global_store_dwordx4 v[18:19], v[14:17], off
	global_load_dwordx4 v[144:147], v[48:49], off offset:16
	global_load_dwordx4 v[148:151], v[48:49], off
	v_lshlrev_b32_e32 v20, 16, v12
	v_and_b32_e32 v12, 0xffff0000, v12
	v_lshlrev_b32_e32 v14, 16, v10
	v_and_b32_e32 v10, 0xffff0000, v10
	v_mul_f32_e32 v10, 0xbfb8aa3b, v10
	v_exp_f32_e32 v10, v10
	v_lshlrev_b32_e32 v15, 16, v11
	v_and_b32_e32 v11, 0xffff0000, v11
	v_lshlrev_b32_e32 v22, 16, v13
	v_add_f32_e32 v10, 1.0, v10
	v_rcp_f32_e32 v17, v10
	v_mul_f32_e32 v10, 0xbfb8aa3b, v15
	v_exp_f32_e32 v10, v10
	v_and_b32_e32 v13, 0xffff0000, v13
	v_mul_f32_e32 v14, 0xbfb8aa3b, v14
	v_exp_f32_e32 v14, v14
	v_add_f32_e32 v10, 1.0, v10
	v_rcp_f32_e32 v18, v10
	v_mul_f32_e32 v10, 0xbfb8aa3b, v11
	v_exp_f32_e32 v10, v10
	v_and_b32_e32 v11, 0xffff0000, v5
	v_add_f32_e32 v14, 1.0, v14
	v_rcp_f32_e32 v16, v14
	v_add_f32_e32 v10, 1.0, v10
	v_rcp_f32_e32 v19, v10
	v_mul_f32_e32 v10, 0xbfb8aa3b, v20
	v_exp_f32_e32 v10, v10
	v_lshlrev_b32_e32 v30, 16, v3
	v_and_b32_e32 v31, 0xffff0000, v3
	v_lshlrev_b32_e32 v34, 16, v2
	v_add_f32_e32 v10, 1.0, v10
	v_rcp_f32_e32 v20, v10
	v_mul_f32_e32 v10, 0xbfb8aa3b, v12
	v_exp_f32_e32 v10, v10
	v_lshlrev_b32_e32 v12, 16, v9
	v_and_b32_e32 v35, 0xffff0000, v2
	v_lshlrev_b32_e32 v2, 16, v6
	v_add_f32_e32 v10, 1.0, v10
	v_rcp_f32_e32 v21, v10
	v_mul_f32_e32 v10, 0xbfb8aa3b, v22
	v_exp_f32_e32 v10, v10
	v_and_b32_e32 v3, 0xffff0000, v6
	v_lshlrev_b32_e32 v32, 16, v7
	v_and_b32_e32 v33, 0xffff0000, v7
	v_add_f32_e32 v10, 1.0, v10
	v_rcp_f32_e32 v22, v10
	v_mul_f32_e32 v10, 0xbfb8aa3b, v13
	v_exp_f32_e32 v10, v10
	v_and_b32_e32 v13, 0xffff0000, v9
	v_pk_add_f32 v[2:3], v[34:35], v[2:3]
	v_pk_add_f32 v[30:31], v[30:31], v[32:33]
	v_add_f32_e32 v10, 1.0, v10
	v_rcp_f32_e32 v23, v10
	v_lshlrev_b32_e32 v10, 16, v5
	v_pk_add_f32 v[24:25], v[10:11], v[12:13]
	v_lshlrev_b32_e32 v10, 16, v4
	v_and_b32_e32 v11, 0xffff0000, v4
	v_lshlrev_b32_e32 v4, 16, v8
	v_and_b32_e32 v5, 0xffff0000, v8
	v_pk_add_f32 v[4:5], v[10:11], v[4:5]
	s_nop 0
	s_nop 0
	v_pk_mul_f32 v[6:7], v[2:3], v[2:3]
	v_pk_mul_f32 v[32:33], v[30:31], v[30:31]
	v_add_f32_e32 v6, v6, v7
	v_add_f32_e32 v6, v32, v6
	v_pk_mul_f32 v[28:29], v[4:5], v[4:5]
	v_add_f32_e32 v6, v33, v6
	v_add_f32_e32 v6, v28, v6
	v_pk_mul_f32 v[26:27], v[24:25], v[24:25]
	v_add_f32_e32 v6, v29, v6
	v_add_f32_e32 v6, v26, v6
	v_add_f32_e32 v6, v27, v6
	s_nop 1
	v_add_f32_dpp v6, v6, v6 quad_perm:[1,0,3,2] row_mask:0xf bank_mask:0xf bound_ctrl:1
	s_nop 1
	v_add_f32_dpp v6, v6, v6 quad_perm:[2,3,0,1] row_mask:0xf bank_mask:0xf bound_ctrl:1
	s_nop 1
	v_add_f32_dpp v6, v6, v6 row_half_mirror row_mask:0xf bank_mask:0xf bound_ctrl:1
	s_nop 1
	v_add_f32_dpp v6, v6, v6 row_mirror row_mask:0xf bank_mask:0xf bound_ctrl:1
	v_fmamk_f32 v6, v6, 0x3c000000, v233
	v_rsq_f32_e32 v6, v6
	s_nop 0
	v_pk_mul_f32 v[2:3], v[2:3], v[6:7] op_sel_hi:[1,0]
	v_pk_mul_f32 v[4:5], v[4:5], v[6:7] op_sel_hi:[1,0]
	s_waitcnt vmcnt(0)
	v_pk_mul_f32 v[2:3], v[148:149], v[2:3]
	v_pk_mul_f32 v[12:13], v[30:31], v[6:7] op_sel_hi:[1, 0]
	v_pk_mul_f32 v[6:7], v[24:25], v[6:7] op_sel_hi:[1,0]
	v_pk_mul_f32 v[4:5], v[144:145], v[4:5]
	v_pk_mul_f32 v[6:7], v[6:7], v[146:147]
	v_pk_mul_f32 v[12:13], v[150:151], v[12:13]
	v_pk_mul_f32 v[4:5], v[20:21], v[4:5]
	v_pk_mul_f32 v[6:7], v[22:23], v[6:7]
	v_pk_mul_f32 v[2:3], v[16:17], v[2:3]
	v_pk_mul_f32 v[12:13], v[18:19], v[12:13]
	v_cvt_pk_bf16_f32 v4, v4, v5
	v_cvt_pk_bf16_f32 v5, v6, v7
	v_lshlrev_b64 v[6:7], 12, v[50:51]
	v_cvt_pk_bf16_f32 v2, v2, v3
	v_cvt_pk_bf16_f32 v3, v12, v13
	v_lshl_add_u64 v[6:7], v[46:47], 0, v[6:7]
	global_store_dwordx4 v[6:7], v[2:5], off
	v_mov_b32_e32 v11, v147
	v_mov_b32_e32 v72, v88
	v_mov_b32_e32 v73, v89
	v_mov_b32_e32 v74, v90
	v_mov_b32_e32 v75, v91
	s_cbranch_vccnz .LBB0_463
	s_branch .LBB0_403

.LBB0_616:
	global_load_dwordx4 v[2:5], v[10:11], off offset:16
	global_load_dwordx4 v[6:9], v[10:11], off
	v_lshl_add_u64 v[12:13], s[8:9], 0, v[0:1]
	v_add_co_u32_e32 v26, vcc, 0x49200000, v12
	v_lshl_add_u64 v[14:15], s[6:7], 0, v[0:1]
	s_nop 0
	v_addc_co_u32_e32 v27, vcc, 0, v13, vcc
	global_load_dwordx4 v[50:53], v[26:27], off
	v_add_co_u32_e32 v30, vcc, 0x4a600000, v12
	v_lshl_add_u64 v[18:19], s[2:3], 0, v[0:1]
	s_mov_b32 s1, 0x25e00000
	v_addc_co_u32_e32 v31, vcc, 0, v13, vcc
	global_load_dwordx4 v[22:25], v[30:31], off
	v_add_co_u32_e64 v28, s[4:5], s1, v18
	v_add_co_u32_e32 v32, vcc, 0x1fa01000, v14
	s_nop 0
	s_nop 0
	v_addc_co_u32_e64 v29, s[4:5], 0, v19, s[4:5]
	s_nop 0
	s_nop 0
	v_addc_co_u32_e32 v33, vcc, 0, v15, vcc
	global_load_dwordx4 v[12:15], v[32:33], off offset:2048
	s_add_i32 s0, s0, s82
	s_add_u32 s2, s2, s56
	s_addc_u32 s3, s3, s57
	s_add_u32 s6, s6, s10
	s_addc_u32 s7, s7, s11
	s_add_u32 s8, s8, s28
	s_addc_u32 s9, s9, s29
	s_cmpk_gt_i32 s0, 0x27ff
	s_waitcnt vmcnt(2)
	v_lshlrev_b32_e32 v34, 16, v53
	v_and_b32_e32 v35, 0xffff0000, v53
	v_lshlrev_b32_e32 v36, 16, v52
	v_and_b32_e32 v37, 0xffff0000, v52
	v_lshlrev_b32_e32 v20, 16, v51
	v_and_b32_e32 v21, 0xffff0000, v51
	v_lshlrev_b32_e32 v38, 16, v50
	v_and_b32_e32 v39, 0xffff0000, v50
	s_waitcnt vmcnt(1)
	v_lshlrev_b32_e32 v18, 16, v25
	v_and_b32_e32 v19, 0xffff0000, v25
	v_lshlrev_b32_e32 v40, 16, v24
	v_and_b32_e32 v41, 0xffff0000, v24
	v_lshlrev_b32_e32 v24, 16, v23
	v_and_b32_e32 v25, 0xffff0000, v23
	v_lshlrev_b32_e32 v42, 16, v22
	v_and_b32_e32 v43, 0xffff0000, v22
	s_waitcnt vmcnt(0)
	v_lshlrev_b32_e32 v17, 16, v12
	v_and_b32_e32 v22, 0xffff0000, v12
	v_lshlrev_b32_e32 v23, 16, v13
	v_and_b32_e32 v44, 0xffff0000, v13
	v_lshlrev_b32_e32 v45, 16, v14
	v_pk_add_f32 v[12:13], v[34:35], v[18:19]
	v_pk_add_f32 v[18:19], v[20:21], v[24:25]
	v_pk_add_f32 v[20:21], v[38:39], v[42:43]
	v_and_b32_e32 v46, 0xffff0000, v14
	v_lshlrev_b32_e32 v47, 16, v15
	v_and_b32_e32 v48, 0xffff0000, v15
	v_pk_add_f32 v[14:15], v[36:37], v[40:41]
	v_mul_f32_e32 v17, 0xbfb8aa3b, v17
	v_mul_f32_e32 v41, 0xbfb8aa3b, v45
	v_pk_mul_f32 v[36:37], v[20:21], v[20:21]
	v_pk_mul_f32 v[34:35], v[18:19], v[18:19]
	v_exp_f32_e32 v17, v17
	v_exp_f32_e32 v41, v41
	v_add_f32_e32 v36, v36, v37
	v_add_f32_e32 v34, v34, v36
	v_pk_mul_f32 v[24:25], v[14:15], v[14:15]
	v_add_f32_e32 v34, v35, v34
	v_add_f32_e32 v24, v24, v34
	v_mul_f32_e32 v38, 0xbfb8aa3b, v22
	v_mul_f32_e32 v39, 0xbfb8aa3b, v23
	v_pk_mul_f32 v[22:23], v[12:13], v[12:13]
	v_add_f32_e32 v17, 1.0, v17
	v_add_f32_e32 v37, 1.0, v41
	v_add_f32_e32 v41, v25, v24
	v_rcp_f32_e32 v24, v17
	v_add_f32_e32 v17, v22, v41
	v_add_f32_e32 v17, v23, v17
	v_mul_f32_e32 v40, 0xbfb8aa3b, v44
	v_mul_f32_e32 v42, 0xbfb8aa3b, v46
	v_add_f32_dpp v17, v17, v17 quad_perm:[1,0,3,2] row_mask:0xf bank_mask:0xf bound_ctrl:1
	v_mul_f32_e32 v43, 0xbfb8aa3b, v47
	v_mul_f32_e32 v44, 0xbfb8aa3b, v48
	v_add_f32_dpp v17, v17, v17 quad_perm:[2,3,0,1] row_mask:0xf bank_mask:0xf bound_ctrl:1
	v_exp_f32_e32 v38, v38
	v_exp_f32_e32 v39, v39
	v_exp_f32_e32 v40, v40
	v_exp_f32_e32 v42, v42
	v_exp_f32_e32 v43, v43
	v_exp_f32_e32 v44, v44
	v_add_f32_dpp v17, v17, v17 row_half_mirror row_mask:0xf bank_mask:0xf bound_ctrl:1
	v_add_f32_e32 v34, 1.0, v38
	v_add_f32_e32 v35, 1.0, v39
	v_add_f32_dpp v17, v17, v17 row_mirror row_mask:0xf bank_mask:0xf bound_ctrl:1
	v_fmamk_f32 v17, v17, 0x3c000000, v233
	v_rsq_f32_e32 v22, v17
	v_add_f32_e32 v36, 1.0, v40
	v_add_f32_e32 v38, 1.0, v42
	v_add_f32_e32 v39, 1.0, v43
	v_add_f32_e32 v40, 1.0, v44
	v_rcp_f32_e32 v25, v34
	v_rcp_f32_e32 v34, v35
	v_rcp_f32_e32 v35, v36
	v_rcp_f32_e32 v36, v37
	v_rcp_f32_e32 v37, v38
	v_rcp_f32_e32 v38, v39
	v_rcp_f32_e32 v39, v40
	v_pk_mul_f32 v[20:21], v[20:21], v[22:23] op_sel_hi:[1,0]
	v_pk_mul_f32 v[18:19], v[18:19], v[22:23] op_sel_hi:[1,0]
	v_pk_mul_f32 v[14:15], v[14:15], v[22:23] op_sel_hi:[1,0]
	v_pk_mul_f32 v[12:13], v[12:13], v[22:23] op_sel_hi:[1,0]
	v_pk_mul_f32 v[6:7], v[6:7], v[20:21]
	v_pk_mul_f32 v[8:9], v[8:9], v[18:19]
	v_pk_mul_f32 v[2:3], v[2:3], v[14:15]
	v_pk_mul_f32 v[4:5], v[4:5], v[12:13]
	v_pk_mul_f32 v[6:7], v[24:25], v[6:7]
	v_pk_mul_f32 v[8:9], v[34:35], v[8:9]
	v_pk_mul_f32 v[12:13], v[36:37], v[2:3]
	v_pk_mul_f32 v[14:15], v[38:39], v[4:5]
	v_cvt_pk_bf16_f32 v2, v6, v7
	v_cvt_pk_bf16_f32 v3, v8, v9
	v_cvt_pk_bf16_f32 v4, v12, v13
	v_cvt_pk_bf16_f32 v5, v14, v15
	global_store_dwordx4 v[28:29], v[2:5], off
	global_load_dwordx4 v[2:5], v[26:27], off offset:1024
	global_load_dwordx4 v[6:9], v[30:31], off offset:1024
	global_load_dwordx4 v[12:15], v[32:33], off offset:3072
	global_load_dwordx4 v[18:21], v[10:11], off offset:16
	global_load_dwordx4 v[22:25], v[10:11], off
	s_nop 0
	s_nop 0
	s_nop 0
	s_nop 0
	s_nop 0
	s_waitcnt vmcnt(4)
	v_lshlrev_b32_e32 v26, 16, v4
	v_and_b32_e32 v27, 0xffff0000, v4
	s_waitcnt vmcnt(2)
	v_lshlrev_b32_e32 v17, 16, v12
	v_and_b32_e32 v34, 0xffff0000, v12
	v_lshlrev_b32_e32 v35, 16, v13
	v_and_b32_e32 v36, 0xffff0000, v13
	v_lshlrev_b32_e32 v37, 16, v14
	v_and_b32_e32 v38, 0xffff0000, v14
	v_lshlrev_b32_e32 v39, 16, v15
	v_and_b32_e32 v40, 0xffff0000, v15
	v_lshlrev_b32_e32 v12, 16, v5
	v_and_b32_e32 v13, 0xffff0000, v5
	v_lshlrev_b32_e32 v14, 16, v9
	v_and_b32_e32 v15, 0xffff0000, v9
	v_lshlrev_b32_e32 v4, 16, v8
	v_and_b32_e32 v5, 0xffff0000, v8
	v_lshlrev_b32_e32 v8, 16, v3
	v_and_b32_e32 v9, 0xffff0000, v3
	v_lshlrev_b32_e32 v32, 16, v2
	v_and_b32_e32 v33, 0xffff0000, v2
	v_lshlrev_b32_e32 v2, 16, v6
	v_and_b32_e32 v3, 0xffff0000, v6
	v_lshlrev_b32_e32 v30, 16, v7
	v_and_b32_e32 v31, 0xffff0000, v7
	v_pk_add_f32 v[2:3], v[32:33], v[2:3]
	v_pk_add_f32 v[8:9], v[8:9], v[30:31]
	v_pk_mul_f32 v[30:31], v[2:3], v[2:3]
	v_pk_add_f32 v[4:5], v[26:27], v[4:5]
	v_pk_mul_f32 v[26:27], v[8:9], v[8:9]
	v_add_f32_e32 v30, v30, v31
	v_add_f32_e32 v26, v26, v30
	v_pk_add_f32 v[6:7], v[12:13], v[14:15]
	v_pk_mul_f32 v[14:15], v[4:5], v[4:5]
	v_add_f32_e32 v26, v27, v26
	v_add_f32_e32 v14, v14, v26
	v_pk_mul_f32 v[12:13], v[6:7], v[6:7]
	v_add_f32_e32 v14, v15, v14
	v_add_f32_e32 v12, v12, v14
	v_add_f32_e32 v12, v13, v12
	v_mul_f32_e32 v17, 0xbfb8aa3b, v17
	v_mul_f32_e32 v34, 0xbfb8aa3b, v34
	v_add_f32_dpp v12, v12, v12 quad_perm:[1,0,3,2] row_mask:0xf bank_mask:0xf bound_ctrl:1
	v_mul_f32_e32 v35, 0xbfb8aa3b, v35
	v_mul_f32_e32 v36, 0xbfb8aa3b, v36
	v_mul_f32_e32 v37, 0xbfb8aa3b, v37
	v_mul_f32_e32 v38, 0xbfb8aa3b, v38
	v_mul_f32_e32 v39, 0xbfb8aa3b, v39
	v_mul_f32_e32 v40, 0xbfb8aa3b, v40
	v_add_f32_dpp v12, v12, v12 quad_perm:[2,3,0,1] row_mask:0xf bank_mask:0xf bound_ctrl:1
	v_exp_f32_e32 v17, v17
	v_exp_f32_e32 v32, v34
	v_exp_f32_e32 v33, v35
	v_exp_f32_e32 v34, v36
	v_exp_f32_e32 v35, v37
	v_exp_f32_e32 v36, v38
	v_exp_f32_e32 v37, v39
	v_exp_f32_e32 v38, v40
	v_add_f32_dpp v12, v12, v12 row_half_mirror row_mask:0xf bank_mask:0xf bound_ctrl:1
	v_add_f32_e32 v17, 1.0, v17
	v_add_f32_e32 v27, 1.0, v32
	v_add_f32_dpp v12, v12, v12 row_mirror row_mask:0xf bank_mask:0xf bound_ctrl:1
	v_fmamk_f32 v12, v12, 0x3c000000, v233
	v_rsq_f32_e32 v12, v12
	v_add_f32_e32 v30, 1.0, v33
	v_add_f32_e32 v31, 1.0, v34
	v_add_f32_e32 v32, 1.0, v35
	v_add_f32_e32 v33, 1.0, v36
	v_add_f32_e32 v34, 1.0, v37
	v_add_f32_e32 v35, 1.0, v38
	v_rcp_f32_e32 v26, v17
	v_rcp_f32_e32 v27, v27
	v_rcp_f32_e32 v30, v30
	v_rcp_f32_e32 v31, v31
	v_rcp_f32_e32 v32, v32
	v_rcp_f32_e32 v33, v33
	v_rcp_f32_e32 v34, v34
	v_rcp_f32_e32 v35, v35
	v_pk_mul_f32 v[2:3], v[2:3], v[12:13] op_sel_hi:[1,0]
	v_pk_mul_f32 v[8:9], v[8:9], v[12:13] op_sel_hi:[1,0]
	v_pk_mul_f32 v[4:5], v[4:5], v[12:13] op_sel_hi:[1,0]
	v_pk_mul_f32 v[6:7], v[6:7], v[12:13] op_sel_hi:[1,0]
	s_waitcnt vmcnt(0)
	v_pk_mul_f32 v[2:3], v[22:23], v[2:3]
	v_pk_mul_f32 v[8:9], v[24:25], v[8:9]
	v_pk_mul_f32 v[4:5], v[18:19], v[4:5]
	v_pk_mul_f32 v[6:7], v[20:21], v[6:7]
	v_pk_mul_f32 v[2:3], v[26:27], v[2:3]
	v_pk_mul_f32 v[8:9], v[30:31], v[8:9]
	v_pk_mul_f32 v[4:5], v[32:33], v[4:5]
	v_pk_mul_f32 v[6:7], v[34:35], v[6:7]
	v_cvt_pk_bf16_f32 v2, v2, v3
	v_cvt_pk_bf16_f32 v3, v8, v9
	v_cvt_pk_bf16_f32 v4, v4, v5
	v_cvt_pk_bf16_f32 v5, v6, v7
	global_store_dwordx4 v[28:29], v[2:5], off offset:1024
	s_cbranch_scc0 .LBB0_616

.LBB0_655:
	s_lshr_b32 s30, s29, 6
	s_and_b32 s31, s16, 63
	v_mov_b32_e32 v0, s31
	v_mov_b32_e32 v52, s30
	v_cndmask_b32_e64 v0, v0, v52, s[6:7]
	v_lshl_or_b32 v58, v0, 5, v70
	v_lshlrev_b32_e32 v0, 3, v58
	v_lshl_add_u64 v[66:67], s[0:1], 0, v[0:1]
	v_or_b32_e32 v0, 2, v58
	v_lshl_add_u64 v[68:69], v[0:1], 3, s[0:1]
	v_or_b32_e32 v0, 4, v58
	v_lshl_add_u64 v[62:63], v[0:1], 3, s[0:1]
	v_or_b32_e32 v0, 6, v58
	v_lshl_add_u64 v[64:65], v[0:1], 3, s[0:1]
	v_or_b32_e32 v0, 8, v58
	v_lshl_add_u64 v[54:55], v[0:1], 3, s[0:1]
	v_or_b32_e32 v0, 10, v58
	v_lshl_add_u64 v[60:61], v[0:1], 3, s[0:1]
	v_or_b32_e32 v0, 12, v58
	v_lshl_add_u64 v[52:53], v[0:1], 3, s[0:1]
	v_or_b32_e32 v0, 14, v58
	s_andn2_b64 vcc, exec, s[12:13]
	v_lshl_add_u64 v[58:59], v[0:1], 3, s[0:1]
	s_cbranch_vccnz .LBB0_657
	global_load_dwordx2 v[80:81], v[66:67], off
	global_load_dwordx2 v[82:83], v[68:69], off
	s_nop 0
	v_mov_b32_dpp v72, v22 quad_perm:[2,3,0,1] row_mask:0xf bank_mask:0xf bound_ctrl:1
	v_mov_b32_dpp v73, v23 quad_perm:[2,3,0,1] row_mask:0xf bank_mask:0xf bound_ctrl:1
	v_mov_b32_dpp v74, v24 quad_perm:[2,3,0,1] row_mask:0xf bank_mask:0xf bound_ctrl:1
	v_mov_b32_dpp v75, v25 quad_perm:[2,3,0,1] row_mask:0xf bank_mask:0xf bound_ctrl:1
	v_mov_b32_dpp v76, v18 quad_perm:[2,3,0,1] row_mask:0xf bank_mask:0xf bound_ctrl:1
	v_mov_b32_dpp v77, v19 quad_perm:[2,3,0,1] row_mask:0xf bank_mask:0xf bound_ctrl:1
	v_mov_b32_dpp v78, v20 quad_perm:[2,3,0,1] row_mask:0xf bank_mask:0xf bound_ctrl:1
	v_mov_b32_dpp v79, v21 quad_perm:[2,3,0,1] row_mask:0xf bank_mask:0xf bound_ctrl:1
	v_lshlrev_b32_e32 v0, 1, v26
	s_waitcnt vmcnt(1)
	v_mov_b32_e32 v84, v81
	s_waitcnt vmcnt(0)
	v_mov_b32_e32 v85, v83
	v_pk_mul_f32 v[72:73], v[84:85], v[72:73]
	v_mov_b32_e32 v81, v82
	v_cndmask_b32_e64 v73, v73, -v73, s[10:11]
	v_cndmask_b32_e64 v72, v72, -v72, s[10:11]
	v_pk_fma_f32 v[22:23], v[80:81], v[22:23], v[72:73]
	global_load_dwordx2 v[72:73], v[62:63], off
	global_load_dwordx2 v[80:81], v[64:65], off
	s_nop 0
	s_waitcnt vmcnt(1)
	v_mov_b32_e32 v82, v73
	s_waitcnt vmcnt(0)
	v_mov_b32_e32 v83, v81
	v_pk_mul_f32 v[74:75], v[82:83], v[74:75]
	v_mov_b32_e32 v73, v80
	v_cndmask_b32_e64 v75, v75, -v75, s[10:11]
	v_cndmask_b32_e64 v74, v74, -v74, s[10:11]
	v_pk_fma_f32 v[24:25], v[72:73], v[24:25], v[74:75]
	global_load_dwordx2 v[72:73], v[54:55], off
	global_load_dwordx2 v[74:75], v[60:61], off
	s_nop 0
	s_waitcnt vmcnt(1)
	v_mov_b32_e32 v80, v73
	s_waitcnt vmcnt(0)
	v_mov_b32_e32 v81, v75
	v_pk_mul_f32 v[76:77], v[80:81], v[76:77]
	v_mov_b32_e32 v73, v74
	v_cndmask_b32_e64 v75, v77, -v77, s[10:11]
	v_cndmask_b32_e64 v74, v76, -v76, s[10:11]
	v_pk_fma_f32 v[72:73], v[72:73], v[18:19], v[74:75]
	global_load_dwordx2 v[18:19], v[52:53], off
	global_load_dwordx2 v[74:75], v[58:59], off
	s_nop 0
	s_waitcnt vmcnt(1)
	v_mov_b32_e32 v76, v19
	s_waitcnt vmcnt(0)
	v_mov_b32_e32 v77, v75
	v_pk_mul_f32 v[76:77], v[76:77], v[78:79]
	v_mov_b32_e32 v19, v74
	v_cndmask_b32_e64 v75, v77, -v77, s[10:11]
	v_cndmask_b32_e64 v74, v76, -v76, s[10:11]
	v_pk_fma_f32 v[74:75], v[18:19], v[20:21], v[74:75]
	v_cvt_pk_bf16_f32 v18, v22, v23
	v_cvt_pk_bf16_f32 v19, v24, v25
	v_cvt_pk_bf16_f32 v20, v72, v73
	v_cvt_pk_bf16_f32 v21, v74, v75
	global_store_dwordx4 v0, v[18:21], s[24:25]

.LBB0_819:
	s_add_u32 s0, s8, s42
	s_addc_u32 s1, s9, s43
	global_load_dword v2, v171, s[0:1]
	global_load_dword v3, v171, s[0:1] offset:256
	global_load_dword v175, v171, s[0:1] offset:512
	global_load_dword v183, v171, s[0:1] offset:768
	s_nop 0
	s_waitcnt vmcnt(2)
	v_mul_f32_e32 v4, v2, v3
	s_nop 1
	v_mov_b32_dpp v4, v4 quad_perm:[1,0,3,2] row_mask:0xf bank_mask:0xf bound_ctrl:1
	v_fmac_f32_e32 v4, v2, v3
	s_nop 1
	v_add_f32_dpp v2, v4, v4 quad_perm:[2,3,0,1] row_mask:0xf bank_mask:0xf bound_ctrl:1
	s_nop 1
	v_add_f32_dpp v2, v2, v2 row_half_mirror row_mask:0xf bank_mask:0xf bound_ctrl:1
	s_nop 1
	v_add_f32_dpp v2, v2, v2 row_mirror row_mask:0xf bank_mask:0xf bound_ctrl:1
	ds_swizzle_b32 v3, v2 offset:swizzle(SWAP,16)
	s_waitcnt lgkmcnt(0)
	v_add_f32_e32 v2, v2, v3
	v_mov_b32_e32 v3, v2
	s_nop 1
	v_permlane32_swap_b32_e32 v2, v3
	v_add_f32_e32 v2, v2, v3
	s_nop 0
	s_nop 0
	v_mul_f32_e32 v2, 0x3fb8aa3b, v2
	v_exp_f32_e32 v2, v2
	s_waitcnt vmcnt(0)
	v_mul_f32_e32 v5, v175, v183
	s_nop 1
	v_mov_b32_dpp v5, v5 quad_perm:[1,0,3,2] row_mask:0xf bank_mask:0xf bound_ctrl:1
	v_fmac_f32_e32 v5, v175, v183
	s_nop 1
	v_add_f32_dpp v175, v5, v5 quad_perm:[2,3,0,1] row_mask:0xf bank_mask:0xf bound_ctrl:1
	s_nop 1
	v_add_f32_dpp v175, v175, v175 row_half_mirror row_mask:0xf bank_mask:0xf bound_ctrl:1
	s_nop 1
	v_add_f32_dpp v175, v175, v175 row_mirror row_mask:0xf bank_mask:0xf bound_ctrl:1
	ds_swizzle_b32 v4, v175 offset:swizzle(SWAP, 16)
	s_waitcnt lgkmcnt(0)
	v_add_f32_e32 v175, v175, v4
	v_mov_b32_e32 v4, v175
	s_nop 1
	v_permlane32_swap_b32_e32 v175, v4
	v_add_f32_e32 v175, v175, v4
	v_mul_f32_e32 v175, 0x3fb8aa3b, v175
	v_exp_f32_e32 v175, v175
	s_nop 0
	v_sub_f32_e32 v2, v2, v175
	v_add_f32_e32 v2, v169, v2
	v_div_scale_f32 v3, s[0:1], v0, v0, v2
	v_rcp_f32_e32 v4, v3
	s_lshl_b64 s[0:1], s[30:31], 2
	s_add_u32 s0, s10, s0
	s_addc_u32 s1, s11, s1
	v_fma_f32 v5, -v3, v4, 1.0
	v_fmac_f32_e32 v4, v5, v4
	v_div_scale_f32 v5, vcc, v2, v0, v2
	v_mul_f32_e32 v6, v5, v4
	v_fma_f32 v7, -v3, v6, v5
	v_fmac_f32_e32 v6, v7, v4
	v_fma_f32 v3, -v3, v6, v5
	v_div_fmas_f32 v3, v3, v4, v6
	v_div_fixup_f32 v14, v3, v0, v2
	v_add_u32_e32 v0, s19, v167
	ds_read_b128 v[152:155], v0 offset:53248
	ds_read_b128 v[132:135], v0 offset:54272
	ds_read_b128 v[120:123], v0 offset:55296
	ds_read_b128 v[108:111], v0 offset:56320
	ds_read_b128 v[96:99], v0 offset:57344
	ds_read_b128 v[84:87], v0 offset:58368
	ds_read_b128 v[6:9], v0 offset:59392
	ds_read_b128 v[2:5], v0 offset:60416
	v_lshlrev_b32_e32 v0, 2, v180
	global_load_dwordx4 v[160:163], v0, s[0:1]
	global_load_dwordx4 v[156:159], v0, s[0:1] offset:32
	global_load_dwordx4 v[148:151], v0, s[0:1] offset:64
	global_load_dwordx4 v[144:147], v0, s[0:1] offset:96
	global_load_dwordx4 v[140:143], v0, s[0:1] offset:128
	global_load_dwordx4 v[136:139], v0, s[0:1] offset:160
	global_load_dwordx4 v[128:131], v0, s[0:1] offset:192
	global_load_dwordx4 v[124:127], v0, s[0:1] offset:224
	global_load_dwordx4 v[116:119], v0, s[0:1] offset:256
	global_load_dwordx4 v[112:115], v0, s[0:1] offset:288
	global_load_dwordx4 v[104:107], v0, s[0:1] offset:320
	global_load_dwordx4 v[100:103], v0, s[0:1] offset:352
	global_load_dwordx4 v[92:95], v0, s[0:1] offset:384
	global_load_dwordx4 v[88:91], v0, s[0:1] offset:416
	global_load_dwordx4 v[80:83], v0, s[0:1] offset:448
	global_load_dwordx4 v[10:13], v0, s[0:1] offset:480
	s_nop 0
	s_nop 0
	s_nop 0
	s_nop 0
	s_nop 0
	s_nop 0
	s_nop 0
	s_nop 0
	s_nop 0
	s_nop 0
	s_nop 0
	s_nop 0
	s_nop 0
	s_nop 0
	s_nop 0
	s_lshl_b32 s0, s18, 5
	s_add_i32 s0, s17, s0
	s_ashr_i32 s1, s0, 31
	s_lshl_b64 s[0:1], s[0:1], 12
	s_add_u32 s0, s51, s0
	s_addc_u32 s1, s52, s1
	s_lshl_b32 s2, s16, 1
	s_waitcnt lgkmcnt(7)
	v_lshlrev_b32_e32 v218, 16, v153
	v_and_b32_e32 v219, 0xffff0000, v153
	s_add_u32 s2, s0, s2
	v_pk_fma_f32 v[218:219], v[66:67], v[14:15], v[218:219] op_sel_hi:[1,0,1] neg_lo:[1,0,0] neg_hi:[1,0,0]
	s_waitcnt lgkmcnt(0)
	v_lshlrev_b32_e32 v208, 16, v5
	v_and_b32_e32 v209, 0xffff0000, v5
	s_addc_u32 s3, s1, 0
	v_lshlrev_b32_e32 v0, 1, v178
	v_pk_fma_f32 v[30:31], v[30:31], v[14:15], v[208:209] op_sel_hi:[1,0,1] neg_lo:[1,0,0] neg_hi:[1,0,0]
	v_lshl_add_u64 v[208:209], s[2:3], 0, v[0:1]
	v_lshlrev_b32_e32 v0, 1, v180
	v_lshl_add_u64 v[208:209], v[208:209], 0, v[0:1]
	s_waitcnt vmcnt(15)
	v_pk_mul_f32 v[66:67], v[162:163], v[218:219]
	v_lshlrev_b32_e32 v162, 16, v152
	v_and_b32_e32 v163, 0xffff0000, v152
	v_pk_fma_f32 v[64:65], v[64:65], v[14:15], v[162:163] op_sel_hi:[1,0,1] neg_lo:[1,0,0] neg_hi:[1,0,0]
	s_waitcnt vmcnt(0)
	v_pk_mul_f32 v[12:13], v[30:31], v[12:13]
	v_mul_f32_e32 v0, v65, v65
	v_pk_fma_f32 v[152:153], v[64:65], v[64:65], v[0:1] op_sel_hi:[1,1,0]
	v_pk_mul_f32 v[64:65], v[160:161], v[64:65]
	v_lshlrev_b32_e32 v160, 16, v155
	v_and_b32_e32 v161, 0xffff0000, v155
	v_pk_fma_f32 v[160:161], v[70:71], v[14:15], v[160:161] op_sel_hi:[1,0,1] neg_lo:[1,0,0] neg_hi:[1,0,0]
	v_pk_fma_f32 v[152:153], v[218:219], v[218:219], v[152:153]
	v_mul_f32_e32 v0, v219, v219
	v_pk_mul_f32 v[70:71], v[160:161], v[158:159]
	v_lshlrev_b32_e32 v158, 16, v154
	v_and_b32_e32 v159, 0xffff0000, v154
	v_pk_add_f32 v[152:153], v[0:1], v[152:153] op_sel_hi:[0,1]
	v_pk_fma_f32 v[154:155], v[68:69], v[14:15], v[158:159] op_sel_hi:[1,0,1] neg_lo:[1,0,0] neg_hi:[1,0,0]
	s_nop 0
	v_pk_mul_f32 v[68:69], v[154:155], v[156:157]
	v_pk_fma_f32 v[152:153], v[154:155], v[154:155], v[152:153]
	v_mul_f32_e32 v0, v155, v155
	v_lshlrev_b32_e32 v154, 16, v133
	v_and_b32_e32 v155, 0xffff0000, v133
	v_pk_add_f32 v[152:153], v[0:1], v[152:153] op_sel_hi:[0,1]
	v_pk_fma_f32 v[154:155], v[74:75], v[14:15], v[154:155] op_sel_hi:[1,0,1] neg_lo:[1,0,0] neg_hi:[1,0,0]
	v_pk_fma_f32 v[152:153], v[160:161], v[160:161], v[152:153]
	v_mul_f32_e32 v0, v161, v161
	v_pk_mul_f32 v[74:75], v[154:155], v[150:151]
	v_lshlrev_b32_e32 v150, 16, v132
	v_and_b32_e32 v151, 0xffff0000, v132
	v_pk_add_f32 v[152:153], v[0:1], v[152:153] op_sel_hi:[0,1]
	v_pk_fma_f32 v[132:133], v[72:73], v[14:15], v[150:151] op_sel_hi:[1,0,1] neg_lo:[1,0,0] neg_hi:[1,0,0]
	s_nop 0
	v_pk_mul_f32 v[72:73], v[132:133], v[148:149]
	v_pk_fma_f32 v[148:149], v[132:133], v[132:133], v[152:153]
	v_mul_f32_e32 v0, v133, v133
	v_pk_add_f32 v[132:133], v[0:1], v[148:149] op_sel_hi:[0,1]
	v_lshlrev_b32_e32 v148, 16, v135
	v_and_b32_e32 v149, 0xffff0000, v135
	v_pk_fma_f32 v[148:149], v[78:79], v[14:15], v[148:149] op_sel_hi:[1,0,1] neg_lo:[1,0,0] neg_hi:[1,0,0]
	v_pk_fma_f32 v[132:133], v[154:155], v[154:155], v[132:133]
	v_mul_f32_e32 v0, v155, v155
	v_pk_mul_f32 v[78:79], v[148:149], v[146:147]
	v_lshlrev_b32_e32 v146, 16, v134
	v_and_b32_e32 v147, 0xffff0000, v134
	v_pk_add_f32 v[132:133], v[0:1], v[132:133] op_sel_hi:[0,1]
	v_pk_fma_f32 v[134:135], v[76:77], v[14:15], v[146:147] op_sel_hi:[1,0,1] neg_lo:[1,0,0] neg_hi:[1,0,0]
	s_nop 0
	v_pk_mul_f32 v[76:77], v[134:135], v[144:145]
	v_pk_fma_f32 v[132:133], v[134:135], v[134:135], v[132:133]
	v_mul_f32_e32 v0, v135, v135
	v_lshlrev_b32_e32 v134, 16, v121
	v_and_b32_e32 v135, 0xffff0000, v121
	v_pk_add_f32 v[132:133], v[0:1], v[132:133] op_sel_hi:[0,1]
	v_pk_fma_f32 v[134:135], v[50:51], v[14:15], v[134:135] op_sel_hi:[1,0,1] neg_lo:[1,0,0] neg_hi:[1,0,0]
	v_pk_fma_f32 v[132:133], v[148:149], v[148:149], v[132:133]
	v_mul_f32_e32 v0, v149, v149
	v_pk_mul_f32 v[50:51], v[134:135], v[142:143]
	v_lshlrev_b32_e32 v142, 16, v120
	v_and_b32_e32 v143, 0xffff0000, v120
	v_pk_add_f32 v[132:133], v[0:1], v[132:133] op_sel_hi:[0,1]
	v_pk_fma_f32 v[120:121], v[48:49], v[14:15], v[142:143] op_sel_hi:[1,0,1] neg_lo:[1,0,0] neg_hi:[1,0,0]
	s_nop 0
	v_pk_fma_f32 v[132:133], v[120:121], v[120:121], v[132:133]
	v_mul_f32_e32 v0, v121, v121
	v_pk_mul_f32 v[48:49], v[120:121], v[140:141]
	v_pk_add_f32 v[120:121], v[0:1], v[132:133] op_sel_hi:[0,1]
	v_pk_fma_f32 v[120:121], v[134:135], v[134:135], v[120:121]
	v_mul_f32_e32 v0, v135, v135
	v_lshlrev_b32_e32 v134, 16, v122
	v_and_b32_e32 v135, 0xffff0000, v122
	v_pk_add_f32 v[120:121], v[0:1], v[120:121] op_sel_hi:[0,1]
	v_lshlrev_b32_e32 v132, 16, v123
	v_and_b32_e32 v133, 0xffff0000, v123
	v_pk_fma_f32 v[122:123], v[52:53], v[14:15], v[134:135] op_sel_hi:[1,0,1] neg_lo:[1,0,0] neg_hi:[1,0,0]
	v_pk_fma_f32 v[132:133], v[54:55], v[14:15], v[132:133] op_sel_hi:[1,0,1] neg_lo:[1,0,0] neg_hi:[1,0,0]
	v_pk_mul_f32 v[52:53], v[122:123], v[136:137]
	v_pk_fma_f32 v[120:121], v[122:123], v[122:123], v[120:121]
	v_mul_f32_e32 v0, v123, v123
	v_lshlrev_b32_e32 v122, 16, v109
	v_and_b32_e32 v123, 0xffff0000, v109
	v_pk_add_f32 v[120:121], v[0:1], v[120:121] op_sel_hi:[0,1]
	v_pk_fma_f32 v[122:123], v[58:59], v[14:15], v[122:123] op_sel_hi:[1,0,1] neg_lo:[1,0,0] neg_hi:[1,0,0]
	v_pk_fma_f32 v[120:121], v[132:133], v[132:133], v[120:121]
	v_mul_f32_e32 v0, v133, v133
	v_pk_mul_f32 v[58:59], v[122:123], v[130:131]
	v_lshlrev_b32_e32 v130, 16, v108
	v_and_b32_e32 v131, 0xffff0000, v108
	v_pk_add_f32 v[120:121], v[0:1], v[120:121] op_sel_hi:[0,1]
	v_pk_fma_f32 v[108:109], v[56:57], v[14:15], v[130:131] op_sel_hi:[1,0,1] neg_lo:[1,0,0] neg_hi:[1,0,0]
	v_pk_mul_f32 v[54:55], v[132:133], v[138:139]
	v_pk_fma_f32 v[120:121], v[108:109], v[108:109], v[120:121]
	v_mul_f32_e32 v0, v109, v109
	v_pk_mul_f32 v[56:57], v[108:109], v[128:129]
	v_pk_add_f32 v[108:109], v[0:1], v[120:121] op_sel_hi:[0,1]
	v_pk_fma_f32 v[108:109], v[122:123], v[122:123], v[108:109]
	v_mul_f32_e32 v0, v123, v123
	v_lshlrev_b32_e32 v122, 16, v110
	v_and_b32_e32 v123, 0xffff0000, v110
	v_pk_add_f32 v[108:109], v[0:1], v[108:109] op_sel_hi:[0,1]
	v_lshlrev_b32_e32 v120, 16, v111
	v_and_b32_e32 v121, 0xffff0000, v111
	v_pk_fma_f32 v[110:111], v[60:61], v[14:15], v[122:123] op_sel_hi:[1,0,1] neg_lo:[1,0,0] neg_hi:[1,0,0]
	v_pk_fma_f32 v[120:121], v[62:63], v[14:15], v[120:121] op_sel_hi:[1,0,1] neg_lo:[1,0,0] neg_hi:[1,0,0]
	v_pk_mul_f32 v[60:61], v[110:111], v[124:125]
	v_pk_fma_f32 v[108:109], v[110:111], v[110:111], v[108:109]
	v_mul_f32_e32 v0, v111, v111
	v_lshlrev_b32_e32 v110, 16, v97
	v_and_b32_e32 v111, 0xffff0000, v97
	v_pk_add_f32 v[108:109], v[0:1], v[108:109] op_sel_hi:[0,1]
	v_pk_fma_f32 v[110:111], v[34:35], v[14:15], v[110:111] op_sel_hi:[1,0,1] neg_lo:[1,0,0] neg_hi:[1,0,0]
	v_pk_fma_f32 v[108:109], v[120:121], v[120:121], v[108:109]
	v_mul_f32_e32 v0, v121, v121
	v_pk_mul_f32 v[34:35], v[110:111], v[118:119]
	v_lshlrev_b32_e32 v118, 16, v96
	v_and_b32_e32 v119, 0xffff0000, v96
	v_pk_add_f32 v[108:109], v[0:1], v[108:109] op_sel_hi:[0,1]
	v_pk_fma_f32 v[96:97], v[32:33], v[14:15], v[118:119] op_sel_hi:[1,0,1] neg_lo:[1,0,0] neg_hi:[1,0,0]
	v_pk_mul_f32 v[62:63], v[120:121], v[126:127]
	v_pk_fma_f32 v[108:109], v[96:97], v[96:97], v[108:109]
	v_mul_f32_e32 v0, v97, v97
	v_pk_mul_f32 v[32:33], v[96:97], v[116:117]
	v_pk_add_f32 v[96:97], v[0:1], v[108:109] op_sel_hi:[0,1]
	v_pk_fma_f32 v[96:97], v[110:111], v[110:111], v[96:97]
	v_mul_f32_e32 v0, v111, v111
	v_lshlrev_b32_e32 v110, 16, v98
	v_and_b32_e32 v111, 0xffff0000, v98
	v_pk_add_f32 v[96:97], v[0:1], v[96:97] op_sel_hi:[0,1]
	v_pk_fma_f32 v[36:37], v[36:37], v[14:15], v[110:111] op_sel_hi:[1,0,1] neg_lo:[1,0,0] neg_hi:[1,0,0]
	v_lshlrev_b32_e32 v108, 16, v99
	v_pk_fma_f32 v[96:97], v[36:37], v[36:37], v[96:97]
	v_mul_f32_e32 v0, v37, v37
	v_and_b32_e32 v109, 0xffff0000, v99
	v_pk_mul_f32 v[98:99], v[36:37], v[112:113]
	v_pk_add_f32 v[36:37], v[0:1], v[96:97] op_sel_hi:[0,1]
	v_lshlrev_b32_e32 v96, 16, v85
	v_and_b32_e32 v97, 0xffff0000, v85
	v_pk_fma_f32 v[108:109], v[38:39], v[14:15], v[108:109] op_sel_hi:[1,0,1] neg_lo:[1,0,0] neg_hi:[1,0,0]
	v_pk_fma_f32 v[42:43], v[42:43], v[14:15], v[96:97] op_sel_hi:[1,0,1] neg_lo:[1,0,0] neg_hi:[1,0,0]
	v_pk_fma_f32 v[36:37], v[108:109], v[108:109], v[36:37]
	v_mul_f32_e32 v0, v109, v109
	v_pk_mul_f32 v[96:97], v[42:43], v[106:107]
	v_lshlrev_b32_e32 v106, 16, v84
	v_and_b32_e32 v107, 0xffff0000, v84
	v_pk_add_f32 v[36:37], v[0:1], v[36:37] op_sel_hi:[0,1]
	v_pk_fma_f32 v[40:41], v[40:41], v[14:15], v[106:107] op_sel_hi:[1,0,1] neg_lo:[1,0,0] neg_hi:[1,0,0]
	v_pk_mul_f32 v[38:39], v[108:109], v[114:115]
	v_pk_fma_f32 v[36:37], v[40:41], v[40:41], v[36:37]
	v_mul_f32_e32 v0, v41, v41
	v_pk_mul_f32 v[84:85], v[40:41], v[104:105]
	v_pk_add_f32 v[36:37], v[0:1], v[36:37] op_sel_hi:[0,1]
	v_lshlrev_b32_e32 v40, 16, v87
	v_and_b32_e32 v41, 0xffff0000, v87
	v_pk_fma_f32 v[36:37], v[42:43], v[42:43], v[36:37]
	v_mul_f32_e32 v0, v43, v43
	v_pk_fma_f32 v[40:41], v[46:47], v[14:15], v[40:41] op_sel_hi:[1,0,1] neg_lo:[1,0,0] neg_hi:[1,0,0]
	v_lshlrev_b32_e32 v46, 16, v86
	v_and_b32_e32 v47, 0xffff0000, v86
	v_pk_add_f32 v[36:37], v[0:1], v[36:37] op_sel_hi:[0,1]
	v_pk_fma_f32 v[44:45], v[44:45], v[14:15], v[46:47] op_sel_hi:[1,0,1] neg_lo:[1,0,0] neg_hi:[1,0,0]
	v_pk_mul_f32 v[42:43], v[40:41], v[102:103]
	v_pk_fma_f32 v[36:37], v[44:45], v[44:45], v[36:37]
	v_mul_f32_e32 v0, v45, v45
	v_pk_add_f32 v[36:37], v[0:1], v[36:37] op_sel_hi:[0,1]
	v_pk_mul_f32 v[46:47], v[44:45], v[100:101]
	v_pk_fma_f32 v[36:37], v[40:41], v[40:41], v[36:37]
	v_mul_f32_e32 v0, v41, v41
	v_lshlrev_b32_e32 v44, 16, v6
	v_and_b32_e32 v45, 0xffff0000, v6
	v_pk_add_f32 v[36:37], v[0:1], v[36:37] op_sel_hi:[0,1]
	v_lshlrev_b32_e32 v40, 16, v7
	v_and_b32_e32 v41, 0xffff0000, v7
	v_pk_fma_f32 v[6:7], v[16:17], v[14:15], v[44:45] op_sel_hi:[1,0,1] neg_lo:[1,0,0] neg_hi:[1,0,0]
	v_pk_fma_f32 v[18:19], v[18:19], v[14:15], v[40:41] op_sel_hi:[1,0,1] neg_lo:[1,0,0] neg_hi:[1,0,0]
	v_pk_fma_f32 v[36:37], v[6:7], v[6:7], v[36:37]
	v_mul_f32_e32 v0, v7, v7
	v_pk_mul_f32 v[16:17], v[6:7], v[92:93]
	v_pk_add_f32 v[6:7], v[0:1], v[36:37] op_sel_hi:[0,1]
	v_pk_fma_f32 v[6:7], v[18:19], v[18:19], v[6:7]
	v_mul_f32_e32 v0, v19, v19
	v_lshlrev_b32_e32 v36, 16, v8
	v_and_b32_e32 v37, 0xffff0000, v8
	v_pk_mul_f32 v[40:41], v[18:19], v[94:95]
	v_pk_add_f32 v[6:7], v[0:1], v[6:7] op_sel_hi:[0,1]
	v_lshlrev_b32_e32 v18, 16, v9
	v_and_b32_e32 v19, 0xffff0000, v9
	v_pk_fma_f32 v[8:9], v[20:21], v[14:15], v[36:37] op_sel_hi:[1,0,1] neg_lo:[1,0,0] neg_hi:[1,0,0]
	v_pk_fma_f32 v[18:19], v[22:23], v[14:15], v[18:19] op_sel_hi:[1,0,1] neg_lo:[1,0,0] neg_hi:[1,0,0]
	v_pk_fma_f32 v[6:7], v[8:9], v[8:9], v[6:7]
	v_mul_f32_e32 v0, v9, v9
	v_pk_mul_f32 v[20:21], v[8:9], v[88:89]
	v_pk_add_f32 v[6:7], v[0:1], v[6:7] op_sel_hi:[0,1]
	v_lshlrev_b32_e32 v8, 16, v3
	v_and_b32_e32 v9, 0xffff0000, v3
	v_pk_fma_f32 v[6:7], v[18:19], v[18:19], v[6:7]
	v_mul_f32_e32 v0, v19, v19
	v_pk_fma_f32 v[8:9], v[26:27], v[14:15], v[8:9] op_sel_hi:[1,0,1] neg_lo:[1,0,0] neg_hi:[1,0,0]
	v_lshlrev_b32_e32 v26, 16, v2
	v_and_b32_e32 v27, 0xffff0000, v2
	v_pk_add_f32 v[6:7], v[0:1], v[6:7] op_sel_hi:[0,1]
	v_pk_fma_f32 v[2:3], v[24:25], v[14:15], v[26:27] op_sel_hi:[1,0,1] neg_lo:[1,0,0] neg_hi:[1,0,0]
	v_pk_mul_f32 v[22:23], v[18:19], v[90:91]
	v_pk_fma_f32 v[6:7], v[2:3], v[2:3], v[6:7]
	v_mul_f32_e32 v0, v3, v3
	v_pk_mul_f32 v[24:25], v[2:3], v[80:81]
	v_pk_add_f32 v[2:3], v[0:1], v[6:7] op_sel_hi:[0,1]
	v_pk_fma_f32 v[2:3], v[8:9], v[8:9], v[2:3]
	v_mul_f32_e32 v0, v9, v9
	v_lshlrev_b32_e32 v6, 16, v4
	v_and_b32_e32 v7, 0xffff0000, v4
	v_pk_add_f32 v[2:3], v[0:1], v[2:3] op_sel_hi:[0,1]
	v_pk_fma_f32 v[4:5], v[28:29], v[14:15], v[6:7] op_sel_hi:[1,0,1] neg_lo:[1,0,0] neg_hi:[1,0,0]
	v_pk_mul_f32 v[18:19], v[8:9], v[82:83]
	v_pk_fma_f32 v[2:3], v[4:5], v[4:5], v[2:3]
	v_mul_f32_e32 v0, v5, v5
	v_pk_add_f32 v[2:3], v[0:1], v[2:3] op_sel_hi:[0,1]
	v_pk_fma_f32 v[2:3], v[30:31], v[30:31], v[2:3]
	v_mul_f32_e32 v0, v31, v31
	v_pk_add_f32 v[2:3], v[0:1], v[2:3] op_sel_hi:[0,1]
	v_mov_b32_e32 v0, v2
	s_nop 1
	v_permlane32_swap_b32_e32 v2, v0
	v_add_f32_e32 v0, v2, v0
	v_fmamk_f32 v0, v0, 0x3c000000, v233
	v_rsq_f32_e32 v0, v0
	v_pk_mul_f32 v[6:7], v[4:5], v[10:11]
	v_mul_f32_e32 v0, v216, v0
	v_pk_mul_f32 v[2:3], v[64:65], v[0:1] op_sel_hi:[1,0]
	v_pk_mul_f32 v[4:5], v[66:67], v[0:1] op_sel_hi:[1,0]
	v_cvt_pk_bf16_f32 v2, v2, v3
	v_cvt_pk_bf16_f32 v3, v4, v5
	global_store_dwordx2 v[208:209], v[2:3], off
	v_pk_mul_f32 v[2:3], v[68:69], v[0:1] op_sel_hi:[1,0]
	v_pk_mul_f32 v[4:5], v[70:71], v[0:1] op_sel_hi:[1,0]
	v_cvt_pk_bf16_f32 v2, v2, v3
	v_cvt_pk_bf16_f32 v3, v4, v5
	global_store_dwordx2 v[208:209], v[2:3], off offset:16
	v_pk_mul_f32 v[2:3], v[72:73], v[0:1] op_sel_hi:[1,0]
	v_pk_mul_f32 v[4:5], v[74:75], v[0:1] op_sel_hi:[1,0]
	v_cvt_pk_bf16_f32 v2, v2, v3
	v_cvt_pk_bf16_f32 v3, v4, v5
	global_store_dwordx2 v[208:209], v[2:3], off offset:32
	v_pk_mul_f32 v[2:3], v[76:77], v[0:1] op_sel_hi:[1,0]
	v_pk_mul_f32 v[4:5], v[78:79], v[0:1] op_sel_hi:[1,0]
	v_cvt_pk_bf16_f32 v2, v2, v3
	v_cvt_pk_bf16_f32 v3, v4, v5
	global_store_dwordx2 v[208:209], v[2:3], off offset:48
	v_pk_mul_f32 v[2:3], v[48:49], v[0:1] op_sel_hi:[1,0]
	v_pk_mul_f32 v[4:5], v[50:51], v[0:1] op_sel_hi:[1,0]
	v_cvt_pk_bf16_f32 v2, v2, v3
	v_cvt_pk_bf16_f32 v3, v4, v5
	global_store_dwordx2 v[208:209], v[2:3], off offset:64
	v_pk_mul_f32 v[2:3], v[52:53], v[0:1] op_sel_hi:[1,0]
	v_pk_mul_f32 v[4:5], v[54:55], v[0:1] op_sel_hi:[1,0]
	v_cvt_pk_bf16_f32 v2, v2, v3
	v_cvt_pk_bf16_f32 v3, v4, v5
	global_store_dwordx2 v[208:209], v[2:3], off offset:80
	v_pk_mul_f32 v[2:3], v[56:57], v[0:1] op_sel_hi:[1,0]
	v_pk_mul_f32 v[4:5], v[58:59], v[0:1] op_sel_hi:[1,0]
	v_cvt_pk_bf16_f32 v2, v2, v3
	v_cvt_pk_bf16_f32 v3, v4, v5
	global_store_dwordx2 v[208:209], v[2:3], off offset:96
	v_pk_mul_f32 v[2:3], v[60:61], v[0:1] op_sel_hi:[1,0]
	v_pk_mul_f32 v[4:5], v[62:63], v[0:1] op_sel_hi:[1,0]
	v_cvt_pk_bf16_f32 v2, v2, v3
	v_cvt_pk_bf16_f32 v3, v4, v5
	global_store_dwordx2 v[208:209], v[2:3], off offset:112
	v_pk_mul_f32 v[2:3], v[32:33], v[0:1] op_sel_hi:[1,0]
	v_pk_mul_f32 v[4:5], v[34:35], v[0:1] op_sel_hi:[1,0]
	v_cvt_pk_bf16_f32 v2, v2, v3
	v_cvt_pk_bf16_f32 v3, v4, v5
	global_store_dwordx2 v[208:209], v[2:3], off offset:128
	v_pk_mul_f32 v[2:3], v[98:99], v[0:1] op_sel_hi:[1,0]
	v_pk_mul_f32 v[4:5], v[38:39], v[0:1] op_sel_hi:[1,0]
	v_cvt_pk_bf16_f32 v2, v2, v3
	v_cvt_pk_bf16_f32 v3, v4, v5
	global_store_dwordx2 v[208:209], v[2:3], off offset:144
	v_pk_mul_f32 v[2:3], v[84:85], v[0:1] op_sel_hi:[1,0]
	v_pk_mul_f32 v[4:5], v[96:97], v[0:1] op_sel_hi:[1,0]
	v_cvt_pk_bf16_f32 v2, v2, v3
	v_cvt_pk_bf16_f32 v3, v4, v5
	global_store_dwordx2 v[208:209], v[2:3], off offset:160
	v_pk_mul_f32 v[2:3], v[46:47], v[0:1] op_sel_hi:[1,0]
	v_pk_mul_f32 v[4:5], v[42:43], v[0:1] op_sel_hi:[1,0]
	v_cvt_pk_bf16_f32 v2, v2, v3
	v_cvt_pk_bf16_f32 v3, v4, v5
	global_store_dwordx2 v[208:209], v[2:3], off offset:176
	v_pk_mul_f32 v[2:3], v[16:17], v[0:1] op_sel_hi:[1,0]
	v_pk_mul_f32 v[4:5], v[40:41], v[0:1] op_sel_hi:[1,0]
	v_cvt_pk_bf16_f32 v2, v2, v3
	v_cvt_pk_bf16_f32 v3, v4, v5
	global_store_dwordx2 v[208:209], v[2:3], off offset:192
	v_pk_mul_f32 v[2:3], v[20:21], v[0:1] op_sel_hi:[1,0]
	v_pk_mul_f32 v[4:5], v[22:23], v[0:1] op_sel_hi:[1,0]
	v_cvt_pk_bf16_f32 v2, v2, v3
	v_cvt_pk_bf16_f32 v3, v4, v5
	global_store_dwordx2 v[208:209], v[2:3], off offset:208
	v_pk_mul_f32 v[2:3], v[24:25], v[0:1] op_sel_hi:[1,0]
	v_pk_mul_f32 v[4:5], v[18:19], v[0:1] op_sel_hi:[1,0]
	v_cvt_pk_bf16_f32 v2, v2, v3
	v_cvt_pk_bf16_f32 v3, v4, v5
	global_store_dwordx2 v[208:209], v[2:3], off offset:224
	v_pk_mul_f32 v[2:3], v[6:7], v[0:1] op_sel_hi:[1,0]
	v_pk_mul_f32 v[4:5], v[12:13], v[0:1] op_sel_hi:[1,0]
	v_cvt_pk_bf16_f32 v2, v2, v3
	s_cbranch_execz .LBB0_716
	s_branch .LBB0_816

.LBB0_1229:
	global_load_dwordx4 v[0:3], v[44:45], off
	global_load_dwordx4 v[4:7], v[44:45], off offset:16
	s_nop 0
	v_pk_mul_f32 v[8:9], v[84:85], v[84:85]
	v_pk_mul_f32 v[10:11], v[86:87], v[86:87]
	v_add_f32_e32 v8, v9, v8
	v_add_f32_e32 v8, v10, v8
	v_pk_mul_f32 v[12:13], v[80:81], v[80:81]
	v_add_f32_e32 v8, v11, v8
	v_add_f32_e32 v8, v12, v8
	v_pk_mul_f32 v[14:15], v[82:83], v[82:83]
	v_add_f32_e32 v8, v13, v8
	v_add_f32_e32 v8, v14, v8
	v_pk_mul_f32 v[16:17], v[76:77], v[76:77]
	v_add_f32_e32 v8, v15, v8
	v_add_f32_e32 v8, v16, v8
	v_pk_mul_f32 v[18:19], v[78:79], v[78:79]
	v_add_f32_e32 v8, v17, v8
	v_add_f32_e32 v8, v18, v8
	v_pk_mul_f32 v[20:21], v[72:73], v[72:73]
	v_add_f32_e32 v8, v19, v8
	v_add_f32_e32 v8, v20, v8
	v_pk_mul_f32 v[22:23], v[74:75], v[74:75]
	v_add_f32_e32 v8, v21, v8
	v_add_f32_e32 v8, v22, v8
	v_pk_mul_f32 v[24:25], v[68:69], v[68:69]
	v_add_f32_e32 v8, v23, v8
	v_add_f32_e32 v8, v24, v8
	v_pk_mul_f32 v[26:27], v[70:71], v[70:71]
	v_add_f32_e32 v8, v25, v8
	v_add_f32_e32 v8, v26, v8
	v_pk_mul_f32 v[28:29], v[64:65], v[64:65]
	v_add_f32_e32 v8, v27, v8
	v_add_f32_e32 v8, v28, v8
	v_pk_mul_f32 v[30:31], v[66:67], v[66:67]
	v_add_f32_e32 v8, v29, v8
	v_add_f32_e32 v8, v30, v8
	v_pk_mul_f32 v[32:33], v[56:57], v[56:57]
	v_add_f32_e32 v8, v31, v8
	v_add_f32_e32 v8, v32, v8
	v_pk_mul_f32 v[34:35], v[60:61], v[60:61]
	v_add_f32_e32 v8, v33, v8
	v_add_f32_e32 v8, v34, v8
	v_pk_mul_f32 v[36:37], v[58:59], v[58:59]
	v_add_f32_e32 v8, v35, v8
	v_add_f32_e32 v8, v36, v8
	v_pk_mul_f32 v[38:39], v[62:63], v[62:63]
	v_add_f32_e32 v8, v37, v8
	v_add_f32_e32 v8, v38, v8
	v_add_f32_e32 v8, v39, v8
	s_add_i32 s2, s2, s82
	v_lshl_add_u64 v[52:53], v[52:53], 0, s[56:57]
	v_add_f32_dpp v8, v8, v8 quad_perm:[1,0,3,2] row_mask:0xf bank_mask:0xf bound_ctrl:1
	s_cmpk_lt_i32 s2, 0x2800
	s_nop 0
	v_add_f32_dpp v8, v8, v8 quad_perm:[2,3,0,1] row_mask:0xf bank_mask:0xf bound_ctrl:1
	s_nop 1
	v_add_f32_dpp v8, v8, v8 row_half_mirror row_mask:0xf bank_mask:0xf bound_ctrl:1
	s_nop 1
	v_add_f32_dpp v8, v8, v8 row_mirror row_mask:0xf bank_mask:0xf bound_ctrl:1
	ds_swizzle_b32 v9, v8 offset:swizzle(SWAP,16)
	s_waitcnt lgkmcnt(0)
	v_add_f32_e32 v8, v8, v9
	v_mov_b32_e32 v9, v8
	s_nop 1
	v_permlane32_swap_b32_e32 v8, v9
	v_add_f32_e32 v8, v8, v9
	v_fmamk_f32 v8, v8, 0x3a000000, v99
	v_rsq_f32_e32 v8, v8
	s_nop 0
	v_pk_mul_f32 v[10:11], v[84:85], v[8:9] op_sel_hi:[1,0]
	v_pk_mul_f32 v[12:13], v[86:87], v[8:9] op_sel_hi:[1,0]
	v_pk_mul_f32 v[14:15], v[80:81], v[8:9] op_sel_hi:[1,0]
	v_pk_mul_f32 v[16:17], v[82:83], v[8:9] op_sel_hi:[1,0]
	s_waitcnt vmcnt(1)
	v_pk_mul_f32 v[2:3], v[2:3], v[12:13]
	v_pk_mul_f32 v[0:1], v[0:1], v[10:11]
	s_waitcnt vmcnt(0)
	v_pk_mul_f32 v[6:7], v[6:7], v[16:17]
	v_pk_mul_f32 v[4:5], v[4:5], v[14:15]
	global_store_dwordx4 v[54:55], v[0:3], off offset:-4096
	global_store_dwordx4 v[54:55], v[4:7], off offset:-4080
	global_load_dwordx4 v[0:3], v[44:45], off offset:2048
	global_load_dwordx4 v[4:7], v[44:45], off offset:2064
	s_nop 0
	s_nop 0
	v_pk_mul_f32 v[10:11], v[78:79], v[8:9] op_sel_hi:[1,0]
	v_pk_mul_f32 v[12:13], v[76:77], v[8:9] op_sel_hi:[1,0]
	v_pk_mul_f32 v[14:15], v[74:75], v[8:9] op_sel_hi:[1,0]
	v_pk_mul_f32 v[16:17], v[72:73], v[8:9] op_sel_hi:[1,0]
	s_waitcnt vmcnt(1)
	v_pk_mul_f32 v[0:1], v[0:1], v[12:13]
	v_pk_mul_f32 v[2:3], v[2:3], v[10:11]
	s_waitcnt vmcnt(0)
	v_pk_mul_f32 v[4:5], v[4:5], v[16:17]
	v_pk_mul_f32 v[6:7], v[6:7], v[14:15]
	global_store_dwordx4 v[54:55], v[0:3], off offset:-2048
	global_store_dwordx4 v[54:55], v[4:7], off offset:-2032
	global_load_dwordx4 v[0:3], v[46:47], off
	global_load_dwordx4 v[4:7], v[46:47], off offset:16
	s_nop 0
	s_nop 0
	v_pk_mul_f32 v[10:11], v[70:71], v[8:9] op_sel_hi:[1,0]
	v_pk_mul_f32 v[12:13], v[68:69], v[8:9] op_sel_hi:[1,0]
	v_pk_mul_f32 v[14:15], v[66:67], v[8:9] op_sel_hi:[1,0]
	v_pk_mul_f32 v[16:17], v[64:65], v[8:9] op_sel_hi:[1,0]
	s_waitcnt vmcnt(1)
	v_pk_mul_f32 v[0:1], v[12:13], v[0:1]
	v_pk_mul_f32 v[2:3], v[10:11], v[2:3]
	s_waitcnt vmcnt(0)
	v_pk_mul_f32 v[4:5], v[16:17], v[4:5]
	v_pk_mul_f32 v[6:7], v[14:15], v[6:7]
	global_store_dwordx4 v[54:55], v[0:3], off
	global_store_dwordx4 v[54:55], v[4:7], off offset:16
	global_load_dwordx4 v[0:3], v[48:49], off
	global_load_dwordx4 v[4:7], v[48:49], off offset:16
	s_nop 0
	s_nop 0
	v_pk_mul_f32 v[10:11], v[60:61], v[8:9] op_sel_hi:[1,0]
	v_pk_mul_f32 v[12:13], v[56:57], v[8:9] op_sel_hi:[1,0]
	v_pk_mul_f32 v[14:15], v[62:63], v[8:9] op_sel_hi:[1,0]
	v_pk_mul_f32 v[8:9], v[58:59], v[8:9] op_sel_hi:[1,0]
	s_waitcnt vmcnt(1)
	v_pk_mul_f32 v[0:1], v[12:13], v[0:1]
	v_pk_mul_f32 v[2:3], v[10:11], v[2:3]
	s_waitcnt vmcnt(0)
	v_pk_mul_f32 v[4:5], v[8:9], v[4:5]
	v_pk_mul_f32 v[6:7], v[14:15], v[6:7]
	global_store_dwordx4 v[54:55], v[0:3], off offset:2048
	global_store_dwordx4 v[54:55], v[4:7], off offset:2064
	v_lshl_add_u64 v[54:55], v[54:55], 0, s[4:5]
	s_cbranch_scc0 .LBB0_1232
.LBB0_1230:
	global_load_dwordx4 v[0:3], v[52:53], off
	global_load_dwordx4 v[4:7], v[52:53], off offset:1024
	global_load_dwordx4 v[8:11], v[52:53], off offset:2048
	global_load_dwordx4 v[12:15], v[52:53], off offset:3072
	s_cmpk_lt_i32 s2, 0x2000
	s_waitcnt vmcnt(0)
	v_and_b32_e32 v85, 0xffff0000, v0
	v_lshlrev_b32_e32 v84, 16, v0
	v_and_b32_e32 v87, 0xffff0000, v1
	v_lshlrev_b32_e32 v86, 16, v1
	v_and_b32_e32 v81, 0xffff0000, v2
	v_lshlrev_b32_e32 v80, 16, v2
	v_and_b32_e32 v83, 0xffff0000, v3
	v_lshlrev_b32_e32 v82, 16, v3
	v_lshlrev_b32_e32 v76, 16, v4
	v_and_b32_e32 v77, 0xffff0000, v4
	v_lshlrev_b32_e32 v78, 16, v5
	v_and_b32_e32 v79, 0xffff0000, v5
	v_lshlrev_b32_e32 v72, 16, v6
	v_and_b32_e32 v73, 0xffff0000, v6
	v_lshlrev_b32_e32 v74, 16, v7
	v_and_b32_e32 v75, 0xffff0000, v7
	v_lshlrev_b32_e32 v68, 16, v8
	v_and_b32_e32 v69, 0xffff0000, v8
	v_lshlrev_b32_e32 v70, 16, v9
	v_and_b32_e32 v71, 0xffff0000, v9
	v_lshlrev_b32_e32 v64, 16, v10
	v_and_b32_e32 v65, 0xffff0000, v10
	v_lshlrev_b32_e32 v66, 16, v11
	v_and_b32_e32 v67, 0xffff0000, v11
	v_lshlrev_b32_e32 v56, 16, v12
	v_and_b32_e32 v57, 0xffff0000, v12
	v_lshlrev_b32_e32 v60, 16, v13
	v_and_b32_e32 v61, 0xffff0000, v13
	v_lshlrev_b32_e32 v58, 16, v14
	v_and_b32_e32 v59, 0xffff0000, v14
	v_lshlrev_b32_e32 v62, 16, v15
	v_and_b32_e32 v63, 0xffff0000, v15
	s_cbranch_scc1 .LBB0_1229
	s_add_i32 s0, s2, 0xffffe000
	s_lshl_b64 s[6:7], s[0:1], 12
	v_lshl_add_u64 v[88:89], v[50:51], 0, s[6:7]
	global_load_dwordx4 v[4:7], v[88:89], off
	global_load_dwordx4 v[0:3], v[88:89], off offset:1024
	v_add_co_u32_e32 v90, vcc, s3, v88
	s_nop 0
	s_nop 0
	v_addc_co_u32_e32 v91, vcc, 0, v89, vcc
	global_load_dwordx4 v[20:23], v[90:91], off
	v_add_co_u32_e32 v92, vcc, s10, v88
	s_nop 0
	s_nop 0
	v_addc_co_u32_e32 v93, vcc, 0, v89, vcc
	global_load_dwordx4 v[8:11], v[92:93], off
	v_add_co_u32_e32 v94, vcc, s11, v88
	s_nop 0
	s_nop 0
	v_addc_co_u32_e32 v95, vcc, 0, v89, vcc
	global_load_dwordx4 v[100:103], v[94:95], off
	s_lshr_b32 s0, s0, 10
	s_add_i32 s0, s0, 1
	s_mul_hi_u32 s7, s0, 0xc000
	s_mul_i32 s0, s0, 0xc000
	s_add_u32 s6, s8, s0
	s_addc_u32 s7, s9, s7
	global_load_dwordx4 v[104:107], v96, s[6:7]
	global_load_dwordx4 v[108:111], v96, s[6:7] offset:16
	global_load_dwordx4 v[24:27], v[90:91], off offset:1024
	global_load_dwordx4 v[16:19], v[92:93], off offset:1024
	global_load_dwordx4 v[12:15], v[94:95], off offset:1024
	global_load_dwordx4 v[32:35], v96, s[6:7] offset:2048
	global_load_dwordx4 v[28:31], v[88:89], off offset:2048
	global_load_dwordx4 v[36:39], v[90:91], off offset:2048
	global_load_dwordx4 v[112:115], v96, s[6:7] offset:2064
	global_load_dwordx4 v[40:43], v[92:93], off offset:2048
	global_load_dwordx4 v[116:119], v97, s[6:7]
	global_load_dwordx4 v[120:123], v[94:95], off offset:2048
	global_load_dwordx4 v[136:139], v97, s[6:7] offset:16
	global_load_dwordx4 v[140:143], v[88:89], off offset:3072
	global_load_dwordx4 v[144:147], v[90:91], off offset:3072
	global_load_dwordx4 v[148:151], v[92:93], off offset:3072
	global_load_dwordx4 v[152:155], v98, s[6:7] offset:16
	global_load_dwordx4 v[156:159], v[94:95], off offset:3072
	global_load_dwordx4 v[160:163], v98, s[6:7]
	s_nop 0
	s_nop 0
	s_nop 0
	s_nop 0
	s_nop 0
	s_nop 0
	s_nop 0
	s_nop 0
	s_nop 0
	s_nop 0
	s_nop 0
	s_waitcnt vmcnt(23)
	v_and_b32_e32 v125, 0xffff0000, v4
	v_lshlrev_b32_e32 v124, 16, v4
	v_and_b32_e32 v127, 0xffff0000, v5
	v_lshlrev_b32_e32 v126, 16, v5
	v_and_b32_e32 v5, 0xffff0000, v6
	v_lshlrev_b32_e32 v4, 16, v6
	v_and_b32_e32 v129, 0xffff0000, v7
	v_lshlrev_b32_e32 v128, 16, v7
	s_waitcnt vmcnt(21)
	v_and_b32_e32 v131, 0xffff0000, v20
	v_lshlrev_b32_e32 v130, 16, v20
	v_and_b32_e32 v133, 0xffff0000, v21
	v_lshlrev_b32_e32 v132, 16, v21
	v_and_b32_e32 v21, 0xffff0000, v22
	v_lshlrev_b32_e32 v20, 16, v22
	v_and_b32_e32 v135, 0xffff0000, v23
	v_lshlrev_b32_e32 v134, 16, v23
	v_pk_add_f32 v[22:23], v[124:125], v[130:131]
	v_pk_add_f32 v[124:125], v[126:127], v[132:133]
	s_waitcnt vmcnt(20)
	v_and_b32_e32 v127, 0xffff0000, v8
	v_lshlrev_b32_e32 v126, 16, v8
	v_and_b32_e32 v131, 0xffff0000, v9
	v_lshlrev_b32_e32 v130, 16, v9
	v_and_b32_e32 v9, 0xffff0000, v10
	v_lshlrev_b32_e32 v8, 16, v10
	v_and_b32_e32 v133, 0xffff0000, v11
	v_lshlrev_b32_e32 v132, 16, v11
	v_pk_add_f32 v[4:5], v[4:5], v[20:21]
	v_pk_add_f32 v[10:11], v[128:129], v[134:135]
	s_waitcnt vmcnt(19)
	v_and_b32_e32 v21, 0xffff0000, v100
	v_lshlrev_b32_e32 v20, 16, v100
	v_and_b32_e32 v129, 0xffff0000, v101
	v_lshlrev_b32_e32 v128, 16, v101
	v_and_b32_e32 v101, 0xffff0000, v102
	v_lshlrev_b32_e32 v100, 16, v102
	v_and_b32_e32 v135, 0xffff0000, v103
	v_lshlrev_b32_e32 v134, 16, v103
	v_pk_add_f32 v[8:9], v[8:9], v[100:101]
	v_pk_add_f32 v[100:101], v[132:133], v[134:135]
	v_pk_add_f32 v[4:5], v[4:5], v[8:9]
	v_lshlrev_b32_e32 v6, 16, v0
	v_and_b32_e32 v7, 0xffff0000, v0
	v_pk_add_f32 v[8:9], v[10:11], v[100:101]
	s_waitcnt vmcnt(17)
	v_pk_fma_f32 v[80:81], v[108:109], v[4:5], v[80:81]
	s_waitcnt vmcnt(16)
	v_lshlrev_b32_e32 v4, 16, v24
	v_and_b32_e32 v5, 0xffff0000, v24
	v_pk_fma_f32 v[82:83], v[110:111], v[8:9], v[82:83]
	s_waitcnt vmcnt(15)
	v_lshlrev_b32_e32 v8, 16, v16
	v_and_b32_e32 v9, 0xffff0000, v16
	v_pk_add_f32 v[4:5], v[6:7], v[4:5]
	s_waitcnt vmcnt(14)
	v_lshlrev_b32_e32 v6, 16, v12
	v_and_b32_e32 v7, 0xffff0000, v12
	v_pk_add_f32 v[6:7], v[8:9], v[6:7]
	v_lshlrev_b32_e32 v0, 16, v1
	v_and_b32_e32 v1, 0xffff0000, v1
	v_lshlrev_b32_e32 v8, 16, v25
	v_and_b32_e32 v9, 0xffff0000, v25
	v_lshlrev_b32_e32 v10, 16, v17
	v_and_b32_e32 v11, 0xffff0000, v17
	v_pk_add_f32 v[0:1], v[0:1], v[8:9]
	v_lshlrev_b32_e32 v8, 16, v13
	v_and_b32_e32 v9, 0xffff0000, v13
	v_pk_add_f32 v[12:13], v[10:11], v[8:9]
	v_lshlrev_b32_e32 v24, 16, v18
	v_pk_add_f32 v[0:1], v[0:1], v[12:13]
	v_lshlrev_b32_e32 v12, 16, v26
	s_waitcnt vmcnt(13)
	v_pk_fma_f32 v[78:79], v[34:35], v[0:1], v[78:79]
	v_lshlrev_b32_e32 v0, 16, v2
	v_and_b32_e32 v1, 0xffff0000, v2
	v_and_b32_e32 v13, 0xffff0000, v26
	v_and_b32_e32 v25, 0xffff0000, v18
	v_pk_add_f32 v[0:1], v[0:1], v[12:13]
	v_lshlrev_b32_e32 v12, 16, v14
	v_and_b32_e32 v13, 0xffff0000, v14
	v_pk_add_f32 v[12:13], v[24:25], v[12:13]
	v_pk_add_f32 v[4:5], v[4:5], v[6:7]
	v_lshlrev_b32_e32 v2, 16, v3
	v_and_b32_e32 v3, 0xffff0000, v3
	v_lshlrev_b32_e32 v16, 16, v27
	v_and_b32_e32 v17, 0xffff0000, v27
	v_lshlrev_b32_e32 v18, 16, v19
	v_and_b32_e32 v19, 0xffff0000, v19
	v_pk_add_f32 v[0:1], v[0:1], v[12:13]
	v_lshlrev_b32_e32 v12, 16, v15
	v_and_b32_e32 v13, 0xffff0000, v15
	v_pk_add_f32 v[20:21], v[126:127], v[20:21]
	v_pk_add_f32 v[102:103], v[130:131], v[128:129]
	v_pk_fma_f32 v[76:77], v[32:33], v[4:5], v[76:77]
	s_nop 0
	s_waitcnt vmcnt(10)
	v_pk_fma_f32 v[72:73], v[112:113], v[0:1], v[72:73]
	v_pk_add_f32 v[0:1], v[2:3], v[16:17]
	v_pk_add_f32 v[2:3], v[18:19], v[12:13]
	v_pk_add_f32 v[20:21], v[22:23], v[20:21]
	v_pk_add_f32 v[22:23], v[124:125], v[102:103]
	v_pk_add_f32 v[0:1], v[0:1], v[2:3]
	v_pk_fma_f32 v[84:85], v[104:105], v[20:21], v[84:85]
	v_pk_fma_f32 v[86:87], v[106:107], v[22:23], v[86:87]
	s_nop 0
	s_nop 0
	s_nop 0
	v_pk_fma_f32 v[74:75], v[114:115], v[0:1], v[74:75]
	s_nop 0
	s_nop 0
	v_lshlrev_b32_e32 v12, 16, v28
	s_nop 0
	v_and_b32_e32 v13, 0xffff0000, v28
	v_lshlrev_b32_e32 v14, 16, v36
	v_and_b32_e32 v15, 0xffff0000, v36
	s_waitcnt vmcnt(9)
	v_lshlrev_b32_e32 v16, 16, v40
	v_and_b32_e32 v17, 0xffff0000, v40
	v_pk_add_f32 v[12:13], v[12:13], v[14:15]
	s_waitcnt vmcnt(7)
	v_lshlrev_b32_e32 v14, 16, v120
	v_and_b32_e32 v15, 0xffff0000, v120
	v_pk_add_f32 v[14:15], v[16:17], v[14:15]
	v_lshlrev_b32_e32 v16, 16, v121
	v_pk_add_f32 v[12:13], v[12:13], v[14:15]
	v_lshlrev_b32_e32 v14, 16, v37
	v_pk_fma_f32 v[68:69], v[116:117], v[12:13], v[68:69]
	v_lshlrev_b32_e32 v12, 16, v29
	v_and_b32_e32 v13, 0xffff0000, v29
	v_and_b32_e32 v15, 0xffff0000, v37
	v_pk_add_f32 v[12:13], v[12:13], v[14:15]
	v_lshlrev_b32_e32 v14, 16, v41
	v_and_b32_e32 v15, 0xffff0000, v41
	v_and_b32_e32 v17, 0xffff0000, v121
	v_pk_add_f32 v[14:15], v[14:15], v[16:17]
	v_lshlrev_b32_e32 v24, 16, v42
	v_pk_add_f32 v[12:13], v[12:13], v[14:15]
	v_lshlrev_b32_e32 v14, 16, v38
	v_pk_fma_f32 v[70:71], v[118:119], v[12:13], v[70:71]
	v_lshlrev_b32_e32 v12, 16, v30
	v_and_b32_e32 v13, 0xffff0000, v30
	v_and_b32_e32 v15, 0xffff0000, v38
	v_and_b32_e32 v25, 0xffff0000, v42
	v_pk_add_f32 v[12:13], v[12:13], v[14:15]
	v_lshlrev_b32_e32 v14, 16, v122
	v_and_b32_e32 v15, 0xffff0000, v122
	v_pk_add_f32 v[14:15], v[24:25], v[14:15]
	v_lshlrev_b32_e32 v16, 16, v31
	v_and_b32_e32 v17, 0xffff0000, v31
	v_lshlrev_b32_e32 v18, 16, v39
	v_and_b32_e32 v19, 0xffff0000, v39
	v_lshlrev_b32_e32 v24, 16, v43
	v_and_b32_e32 v25, 0xffff0000, v43
	v_pk_add_f32 v[12:13], v[12:13], v[14:15]
	v_lshlrev_b32_e32 v14, 16, v123
	v_and_b32_e32 v15, 0xffff0000, v123
	s_waitcnt vmcnt(6)
	v_pk_fma_f32 v[64:65], v[136:137], v[12:13], v[64:65]
	v_pk_add_f32 v[4:5], v[16:17], v[18:19]
	v_pk_add_f32 v[12:13], v[24:25], v[14:15]
	s_waitcnt vmcnt(1)
	v_lshlrev_b32_e32 v14, 16, v156
	v_pk_add_f32 v[4:5], v[4:5], v[12:13]
	v_lshlrev_b32_e32 v12, 16, v148
	v_pk_fma_f32 v[66:67], v[138:139], v[4:5], v[66:67]
	v_lshlrev_b32_e32 v4, 16, v140
	v_and_b32_e32 v5, 0xffff0000, v140
	v_lshlrev_b32_e32 v6, 16, v144
	v_and_b32_e32 v7, 0xffff0000, v144
	v_and_b32_e32 v13, 0xffff0000, v148
	v_and_b32_e32 v15, 0xffff0000, v156
	v_pk_add_f32 v[4:5], v[4:5], v[6:7]
	v_pk_add_f32 v[6:7], v[12:13], v[14:15]
	v_lshlrev_b32_e32 v8, 16, v149
	v_pk_add_f32 v[4:5], v[4:5], v[6:7]
	v_lshlrev_b32_e32 v6, 16, v145
	s_waitcnt vmcnt(0)
	v_pk_fma_f32 v[56:57], v[160:161], v[4:5], v[56:57]
	v_lshlrev_b32_e32 v4, 16, v141
	v_and_b32_e32 v5, 0xffff0000, v141
	v_and_b32_e32 v7, 0xffff0000, v145
	v_and_b32_e32 v9, 0xffff0000, v149
	v_lshlrev_b32_e32 v12, 16, v157
	v_and_b32_e32 v13, 0xffff0000, v157
	v_pk_add_f32 v[4:5], v[4:5], v[6:7]
	v_pk_add_f32 v[6:7], v[8:9], v[12:13]
	v_lshlrev_b32_e32 v8, 16, v150
	v_pk_add_f32 v[4:5], v[4:5], v[6:7]
	v_lshlrev_b32_e32 v6, 16, v146
	v_pk_fma_f32 v[60:61], v[162:163], v[4:5], v[60:61]
	v_lshlrev_b32_e32 v4, 16, v142
	v_and_b32_e32 v5, 0xffff0000, v142
	v_and_b32_e32 v7, 0xffff0000, v146
	v_and_b32_e32 v9, 0xffff0000, v150
	v_lshlrev_b32_e32 v12, 16, v158
	v_and_b32_e32 v13, 0xffff0000, v158
	v_pk_add_f32 v[4:5], v[4:5], v[6:7]
	v_pk_add_f32 v[6:7], v[8:9], v[12:13]
	v_lshlrev_b32_e32 v8, 16, v159
	v_pk_add_f32 v[4:5], v[4:5], v[6:7]
	v_lshlrev_b32_e32 v6, 16, v151
	v_pk_fma_f32 v[58:59], v[152:153], v[4:5], v[58:59]
	v_lshlrev_b32_e32 v0, 16, v143
	v_and_b32_e32 v1, 0xffff0000, v143
	v_lshlrev_b32_e32 v4, 16, v147
	v_and_b32_e32 v5, 0xffff0000, v147
	v_and_b32_e32 v7, 0xffff0000, v151
	v_and_b32_e32 v9, 0xffff0000, v159
	v_pk_add_f32 v[0:1], v[0:1], v[4:5]
	v_pk_add_f32 v[4:5], v[6:7], v[8:9]
	s_nop 0
	v_pk_add_f32 v[0:1], v[0:1], v[4:5]
	s_nop 0
	v_pk_fma_f32 v[62:63], v[154:155], v[0:1], v[62:63]
	s_branch .LBB0_1229
